# scan: per-step decay folded into the staged vectors per 8-step block (state kept divided by the running decay, rescaled every 8 steps), removing one LDS read and two packed ops per step
# speedup vs baseline: 1.0067x; 1.0067x over previous
.Lsc_item:
	v_lshlrev_b32_e32 v164, 2, v0
	v_add_u32_e32 v164, 107008, v164
	v_xor_b32_e32 v164, 16, v164
	ds_write_b32 v164, v169
	s_waitcnt lgkmcnt(0)
	s_barrier
	s_cmp_ge_u32 s7, 4
	s_cbranch_scc1 .Lsc_G
	v_lshlrev_b32_e32 v27, 2, v173
	v_and_b32_e32 v27, 60, v27
	v_lshlrev_b32_e32 v7, 2, v0
	v_bfe_u32 v1, v173, 4, 2
	v_or_b32_e32 v37, v7, v1
	v_lshlrev_b32_e32 v37, 5, v37
	v_and_b32_e32 v36, 7, v173
	v_lshl_add_u32 v37, v36, 2, v37
	v_add_u32_e32 v37, 74240, v37
	v_and_b32_e32 v34, 15, v173
	v_lshlrev_b32_e32 v34, 4, v34
	v_or_b32_e32 v35, v7, v1
	v_mul_u32_u24_e32 v35, 144, v35
	v_add_u32_e32 v35, 69632, v35
	v_mov_b32_e32 v8, 0
	v_mov_b32_e32 v9, 0
	v_mov_b32_e32 v10, 0
	v_mov_b32_e32 v11, 0
	v_add_u32_e32 v48, 34816, v34
	v_add_u32_e32 v49, 2304, v35
	v_add_u32_e32 v50, 0x4000, v37
	v_mov_b32_e32 v51, 0
	v_mov_b32_e32 v52, 107008
	v_mov_b32_e32 v53, v164
	s_mov_b32 s6, 0
	s_mov_b32 s55, 0x100000

.Lsc_S_go:
	ds_read_b128 v[144:147], v34 offset:32768
	ds_read_b128 v[156:159], v35 offset:0
	ds_read_b128 v[76:79], v34 offset:0
	ds_read_b128 v[80:83], v34 offset:256
	ds_read_b128 v[84:87], v34 offset:512
	ds_read_b128 v[88:91], v34 offset:768
	ds_read_b128 v[92:95], v34 offset:1024
	ds_read_b128 v[96:99], v34 offset:1280
	ds_read_b128 v[100:103], v34 offset:1536
	ds_read_b128 v[104:107], v34 offset:1792
	s_waitcnt lgkmcnt(9)
	v_pk_mul_f32 v[24:25], v[10:11], v[144:145]
	v_pk_fma_f32 v[24:25], v[8:9], v[146:147], v[24:25]
	v_add_f32_e32 v24, v24, v25
	s_waitcnt lgkmcnt(7)
	v_pk_fma_f32 v[16:17], v[76:77], v[156:157], v[10:11] op_sel_hi:[1,0,1]
	v_pk_fma_f32 v[18:19], v[78:79], v[156:157], v[8:9] op_sel_hi:[1,0,1]
	v_add_f32_dpp v15, v24, v24 row_ror:8 row_mask:0xf bank_mask:0xf bound_ctrl:1
	ds_read_b128 v[108:111], v34 offset:2048
	ds_read_b128 v[112:115], v34 offset:2304
	v_add_f32_dpp v15, v15, v15 row_ror:4 row_mask:0xf bank_mask:0xf bound_ctrl:1
	ds_read_b128 v[116:119], v34 offset:2560
	ds_read_b128 v[120:123], v34 offset:2816
	v_add_f32_dpp v15, v15, v15 row_ror:2 row_mask:0xf bank_mask:0xf bound_ctrl:1
	s_nop 1
	v_add_f32_dpp v30, v15, v15 row_ror:1 row_mask:0xf bank_mask:0xf bound_ctrl:1
	s_waitcnt lgkmcnt(0)
.Lsc_S_loop:
	s_waitcnt lgkmcnt(6)
	v_pk_fma_f32 v[10:11], v[80:81], v[30:31], v[16:17] op_sel_hi:[1,0,1] neg_lo:[0,1,0] neg_hi:[0,1,0]
	v_pk_fma_f32 v[8:9], v[82:83], v[30:31], v[18:19] op_sel_hi:[1,0,1] neg_lo:[0,1,0] neg_hi:[0,1,0]
	v_pk_mul_f32 v[24:25], v[10:11], v[84:85] op_sel:[0,0] op_sel_hi:[0,1]
	v_pk_fma_f32 v[24:25], v[10:11], v[86:87], v[24:25] op_sel:[1,0,0] op_sel_hi:[1,1,1]
	v_pk_fma_f32 v[24:25], v[8:9], v[88:89], v[24:25] op_sel:[0,0,0] op_sel_hi:[0,1,1]
	v_pk_fma_f32 v[24:25], v[8:9], v[90:91], v[24:25] op_sel:[1,0,0] op_sel_hi:[1,1,1]
	v_pk_fma_f32 v[16:17], v[92:93], v[156:157], v[10:11] op_sel:[0,1,0] op_sel_hi:[1,1,1]
	v_pk_fma_f32 v[18:19], v[94:95], v[156:157], v[8:9] op_sel:[0,1,0] op_sel_hi:[1,1,1]
	v_add_f32_dpp v15, v24, v24 row_ror:8 row_mask:0xf bank_mask:0xf bound_ctrl:1
	v_add_f32_dpp v32, v25, v25 row_ror:8 row_mask:0xf bank_mask:0xf bound_ctrl:1
	ds_read_b128 v[124:127], v34 offset:3072
	v_add_f32_dpp v15, v15, v15 row_ror:4 row_mask:0xf bank_mask:0xf bound_ctrl:1
	ds_read_b128 v[128:131], v34 offset:3328
	ds_read_b128 v[132:135], v34 offset:3584
	v_add_f32_dpp v15, v15, v15 row_ror:2 row_mask:0xf bank_mask:0xf bound_ctrl:1
	ds_read_b128 v[136:139], v34 offset:3840
	ds_read_b128 v[160:163], v35 offset:16
	v_add_f32_dpp v30, v15, v15 row_ror:1 row_mask:0xf bank_mask:0xf bound_ctrl:1
	s_waitcnt lgkmcnt(5)
	v_pk_fma_f32 v[10:11], v[96:97], v[30:31], v[16:17] op_sel_hi:[1,0,1] neg_lo:[0,1,0] neg_hi:[0,1,0]
	v_pk_fma_f32 v[8:9], v[98:99], v[30:31], v[18:19] op_sel_hi:[1,0,1] neg_lo:[0,1,0] neg_hi:[0,1,0]
	v_pk_mul_f32 v[24:25], v[10:11], v[100:101] op_sel:[0,0] op_sel_hi:[0,1]
	v_pk_fma_f32 v[24:25], v[10:11], v[102:103], v[24:25] op_sel:[1,0,0] op_sel_hi:[1,1,1]
	v_pk_fma_f32 v[24:25], v[8:9], v[104:105], v[24:25] op_sel:[0,0,0] op_sel_hi:[0,1,1]
	v_pk_fma_f32 v[24:25], v[8:9], v[106:107], v[24:25] op_sel:[1,0,0] op_sel_hi:[1,1,1]
	v_pk_fma_f32 v[16:17], v[108:109], v[158:159], v[10:11] op_sel_hi:[1,0,1]
	v_pk_fma_f32 v[18:19], v[110:111], v[158:159], v[8:9] op_sel_hi:[1,0,1]
	v_add_f32_dpp v15, v24, v24 row_ror:8 row_mask:0xf bank_mask:0xf bound_ctrl:1
	v_add_f32_dpp v33, v25, v25 row_ror:8 row_mask:0xf bank_mask:0xf bound_ctrl:1
	ds_read_b128 v[76:79], v34 offset:4096
	v_add_f32_dpp v15, v15, v15 row_ror:4 row_mask:0xf bank_mask:0xf bound_ctrl:1
	ds_read_b128 v[80:83], v34 offset:4352
	ds_read_b128 v[84:87], v34 offset:4608
	v_add_f32_dpp v15, v15, v15 row_ror:2 row_mask:0xf bank_mask:0xf bound_ctrl:1
	ds_read_b128 v[88:91], v34 offset:4864
	s_nop 0
	v_add_f32_dpp v30, v15, v15 row_ror:1 row_mask:0xf bank_mask:0xf bound_ctrl:1
	ds_write2st64_b32 v37, v32, v33 offset0:0 offset1:2
	s_waitcnt lgkmcnt(5)
	v_pk_fma_f32 v[10:11], v[112:113], v[30:31], v[16:17] op_sel_hi:[1,0,1] neg_lo:[0,1,0] neg_hi:[0,1,0]
	v_pk_fma_f32 v[8:9], v[114:115], v[30:31], v[18:19] op_sel_hi:[1,0,1] neg_lo:[0,1,0] neg_hi:[0,1,0]
	v_pk_mul_f32 v[24:25], v[10:11], v[116:117] op_sel:[0,0] op_sel_hi:[0,1]
	v_pk_fma_f32 v[24:25], v[10:11], v[118:119], v[24:25] op_sel:[1,0,0] op_sel_hi:[1,1,1]
	v_pk_fma_f32 v[24:25], v[8:9], v[120:121], v[24:25] op_sel:[0,0,0] op_sel_hi:[0,1,1]
	v_pk_fma_f32 v[24:25], v[8:9], v[122:123], v[24:25] op_sel:[1,0,0] op_sel_hi:[1,1,1]
	v_pk_fma_f32 v[16:17], v[124:125], v[158:159], v[10:11] op_sel:[0,1,0] op_sel_hi:[1,1,1]
	v_pk_fma_f32 v[18:19], v[126:127], v[158:159], v[8:9] op_sel:[0,1,0] op_sel_hi:[1,1,1]
	v_add_f32_dpp v15, v24, v24 row_ror:8 row_mask:0xf bank_mask:0xf bound_ctrl:1
	v_add_f32_dpp v32, v25, v25 row_ror:8 row_mask:0xf bank_mask:0xf bound_ctrl:1
	ds_read_b128 v[92:95], v34 offset:5120
	v_add_f32_dpp v15, v15, v15 row_ror:4 row_mask:0xf bank_mask:0xf bound_ctrl:1
	ds_read_b128 v[96:99], v34 offset:5376
	ds_read_b128 v[100:103], v34 offset:5632
	v_add_f32_dpp v15, v15, v15 row_ror:2 row_mask:0xf bank_mask:0xf bound_ctrl:1
	ds_read_b128 v[104:107], v34 offset:5888
	s_nop 0
	v_add_f32_dpp v30, v15, v15 row_ror:1 row_mask:0xf bank_mask:0xf bound_ctrl:1
	s_waitcnt lgkmcnt(4)
	v_pk_fma_f32 v[10:11], v[128:129], v[30:31], v[16:17] op_sel_hi:[1,0,1] neg_lo:[0,1,0] neg_hi:[0,1,0]
	v_pk_fma_f32 v[8:9], v[130:131], v[30:31], v[18:19] op_sel_hi:[1,0,1] neg_lo:[0,1,0] neg_hi:[0,1,0]
	v_pk_mul_f32 v[24:25], v[10:11], v[132:133] op_sel:[0,0] op_sel_hi:[0,1]
	v_pk_fma_f32 v[24:25], v[10:11], v[134:135], v[24:25] op_sel:[1,0,0] op_sel_hi:[1,1,1]
	v_pk_fma_f32 v[24:25], v[8:9], v[136:137], v[24:25] op_sel:[0,0,0] op_sel_hi:[0,1,1]
	v_pk_fma_f32 v[24:25], v[8:9], v[138:139], v[24:25] op_sel:[1,0,0] op_sel_hi:[1,1,1]
	v_pk_fma_f32 v[16:17], v[76:77], v[160:161], v[10:11] op_sel_hi:[1,0,1]
	v_pk_fma_f32 v[18:19], v[78:79], v[160:161], v[8:9] op_sel_hi:[1,0,1]
	v_add_f32_dpp v15, v24, v24 row_ror:8 row_mask:0xf bank_mask:0xf bound_ctrl:1
	v_add_f32_dpp v33, v25, v25 row_ror:8 row_mask:0xf bank_mask:0xf bound_ctrl:1
	ds_read_b128 v[108:111], v34 offset:6144
	v_add_f32_dpp v15, v15, v15 row_ror:4 row_mask:0xf bank_mask:0xf bound_ctrl:1
	ds_read_b128 v[112:115], v34 offset:6400
	ds_read_b128 v[116:119], v34 offset:6656
	v_add_f32_dpp v15, v15, v15 row_ror:2 row_mask:0xf bank_mask:0xf bound_ctrl:1
	ds_read_b128 v[120:123], v34 offset:6912
	ds_read_b128 v[140:143], v34 offset:33792
	v_add_f32_dpp v30, v15, v15 row_ror:1 row_mask:0xf bank_mask:0xf bound_ctrl:1
	ds_write2st64_b32 v37, v32, v33 offset0:4 offset1:6
	s_waitcnt lgkmcnt(6)
	v_pk_fma_f32 v[10:11], v[80:81], v[30:31], v[16:17] op_sel_hi:[1,0,1] neg_lo:[0,1,0] neg_hi:[0,1,0]
	v_pk_fma_f32 v[8:9], v[82:83], v[30:31], v[18:19] op_sel_hi:[1,0,1] neg_lo:[0,1,0] neg_hi:[0,1,0]
	v_pk_mul_f32 v[24:25], v[10:11], v[84:85] op_sel:[0,0] op_sel_hi:[0,1]
	v_pk_fma_f32 v[24:25], v[10:11], v[86:87], v[24:25] op_sel:[1,0,0] op_sel_hi:[1,1,1]
	v_pk_fma_f32 v[24:25], v[8:9], v[88:89], v[24:25] op_sel:[0,0,0] op_sel_hi:[0,1,1]
	v_pk_fma_f32 v[24:25], v[8:9], v[90:91], v[24:25] op_sel:[1,0,0] op_sel_hi:[1,1,1]
	v_pk_fma_f32 v[16:17], v[92:93], v[160:161], v[10:11] op_sel:[0,1,0] op_sel_hi:[1,1,1]
	v_pk_fma_f32 v[18:19], v[94:95], v[160:161], v[8:9] op_sel:[0,1,0] op_sel_hi:[1,1,1]
	v_add_f32_dpp v15, v24, v24 row_ror:8 row_mask:0xf bank_mask:0xf bound_ctrl:1
	v_add_f32_dpp v32, v25, v25 row_ror:8 row_mask:0xf bank_mask:0xf bound_ctrl:1
	ds_read_b128 v[124:127], v34 offset:7168
	v_add_f32_dpp v15, v15, v15 row_ror:4 row_mask:0xf bank_mask:0xf bound_ctrl:1
	ds_read_b128 v[128:131], v34 offset:7424
	ds_read_b128 v[132:135], v34 offset:7680
	v_add_f32_dpp v15, v15, v15 row_ror:2 row_mask:0xf bank_mask:0xf bound_ctrl:1
	ds_read_b128 v[136:139], v34 offset:7936
	ds_read_b128 v[156:159], v35 offset:32
	v_add_f32_dpp v30, v15, v15 row_ror:1 row_mask:0xf bank_mask:0xf bound_ctrl:1
	s_waitcnt lgkmcnt(5)
	v_pk_fma_f32 v[10:11], v[96:97], v[30:31], v[16:17] op_sel_hi:[1,0,1] neg_lo:[0,1,0] neg_hi:[0,1,0]
	v_pk_fma_f32 v[8:9], v[98:99], v[30:31], v[18:19] op_sel_hi:[1,0,1] neg_lo:[0,1,0] neg_hi:[0,1,0]
	v_pk_mul_f32 v[24:25], v[10:11], v[100:101] op_sel:[0,0] op_sel_hi:[0,1]
	v_pk_fma_f32 v[24:25], v[10:11], v[102:103], v[24:25] op_sel:[1,0,0] op_sel_hi:[1,1,1]
	v_pk_fma_f32 v[24:25], v[8:9], v[104:105], v[24:25] op_sel:[0,0,0] op_sel_hi:[0,1,1]
	v_pk_fma_f32 v[24:25], v[8:9], v[106:107], v[24:25] op_sel:[1,0,0] op_sel_hi:[1,1,1]
	v_pk_fma_f32 v[16:17], v[108:109], v[162:163], v[10:11] op_sel_hi:[1,0,1]
	v_pk_fma_f32 v[18:19], v[110:111], v[162:163], v[8:9] op_sel_hi:[1,0,1]
	v_add_f32_dpp v15, v24, v24 row_ror:8 row_mask:0xf bank_mask:0xf bound_ctrl:1
	v_add_f32_dpp v33, v25, v25 row_ror:8 row_mask:0xf bank_mask:0xf bound_ctrl:1
	ds_read_b128 v[76:79], v34 offset:8192
	v_add_f32_dpp v15, v15, v15 row_ror:4 row_mask:0xf bank_mask:0xf bound_ctrl:1
	ds_read_b128 v[80:83], v34 offset:8448
	ds_read_b128 v[84:87], v34 offset:8704
	v_add_f32_dpp v15, v15, v15 row_ror:2 row_mask:0xf bank_mask:0xf bound_ctrl:1
	ds_read_b128 v[88:91], v34 offset:8960
	ds_read_b128 v[144:147], v34 offset:33024
	v_add_f32_dpp v30, v15, v15 row_ror:1 row_mask:0xf bank_mask:0xf bound_ctrl:1
	ds_write2st64_b32 v37, v32, v33 offset0:8 offset1:10
	s_waitcnt lgkmcnt(6)
	v_pk_fma_f32 v[10:11], v[112:113], v[30:31], v[16:17] op_sel_hi:[1,0,1] neg_lo:[0,1,0] neg_hi:[0,1,0]
	v_pk_fma_f32 v[8:9], v[114:115], v[30:31], v[18:19] op_sel_hi:[1,0,1] neg_lo:[0,1,0] neg_hi:[0,1,0]
	v_pk_mul_f32 v[24:25], v[10:11], v[116:117] op_sel:[0,0] op_sel_hi:[0,1]
	v_pk_fma_f32 v[24:25], v[10:11], v[118:119], v[24:25] op_sel:[1,0,0] op_sel_hi:[1,1,1]
	v_pk_fma_f32 v[24:25], v[8:9], v[120:121], v[24:25] op_sel:[0,0,0] op_sel_hi:[0,1,1]
	v_pk_fma_f32 v[24:25], v[8:9], v[122:123], v[24:25] op_sel:[1,0,0] op_sel_hi:[1,1,1]
	v_pk_fma_f32 v[16:17], v[124:125], v[162:163], v[10:11] op_sel:[0,1,0] op_sel_hi:[1,1,1]
	v_pk_fma_f32 v[18:19], v[126:127], v[162:163], v[8:9] op_sel:[0,1,0] op_sel_hi:[1,1,1]
	v_add_f32_dpp v15, v24, v24 row_ror:8 row_mask:0xf bank_mask:0xf bound_ctrl:1
	v_add_f32_dpp v32, v25, v25 row_ror:8 row_mask:0xf bank_mask:0xf bound_ctrl:1
	ds_read_b128 v[92:95], v34 offset:9216
	v_add_f32_dpp v15, v15, v15 row_ror:4 row_mask:0xf bank_mask:0xf bound_ctrl:1
	ds_read_b128 v[96:99], v34 offset:9472
	ds_read_b128 v[100:103], v34 offset:9728
	v_add_f32_dpp v15, v15, v15 row_ror:2 row_mask:0xf bank_mask:0xf bound_ctrl:1
	ds_read_b128 v[104:107], v34 offset:9984
	s_nop 0
	v_add_f32_dpp v30, v15, v15 row_ror:1 row_mask:0xf bank_mask:0xf bound_ctrl:1
	s_waitcnt lgkmcnt(4)
	v_pk_fma_f32 v[10:11], v[128:129], v[30:31], v[16:17] op_sel_hi:[1,0,1] neg_lo:[0,1,0] neg_hi:[0,1,0]
	v_pk_fma_f32 v[8:9], v[130:131], v[30:31], v[18:19] op_sel_hi:[1,0,1] neg_lo:[0,1,0] neg_hi:[0,1,0]
	v_pk_mul_f32 v[24:25], v[10:11], v[132:133] op_sel:[0,0] op_sel_hi:[0,1]
	v_pk_fma_f32 v[24:25], v[10:11], v[134:135], v[24:25] op_sel:[1,0,0] op_sel_hi:[1,1,1]
	v_pk_fma_f32 v[24:25], v[8:9], v[136:137], v[24:25] op_sel:[0,0,0] op_sel_hi:[0,1,1]
	v_pk_fma_f32 v[24:25], v[8:9], v[138:139], v[24:25] op_sel:[1,0,0] op_sel_hi:[1,1,1]
	s_nop 1
	v_add_f32_dpp v33, v25, v25 row_ror:8 row_mask:0xf bank_mask:0xf bound_ctrl:1
	ds_read_b128 v[108:111], v34 offset:10240
	ds_read_b128 v[112:115], v34 offset:10496
	ds_read_b128 v[116:119], v34 offset:10752
	ds_read_b128 v[120:123], v34 offset:11008
	ds_write2st64_b32 v37, v32, v33 offset0:12 offset1:14
	v_pk_mul_f32 v[10:11], v[10:11], v[140:141]
	v_pk_mul_f32 v[8:9], v[8:9], v[142:143]
	v_pk_mul_f32 v[24:25], v[10:11], v[144:145]
	v_pk_fma_f32 v[24:25], v[8:9], v[146:147], v[24:25]
	v_add_f32_e32 v24, v24, v25
	v_pk_fma_f32 v[16:17], v[76:77], v[156:157], v[10:11] op_sel_hi:[1,0,1]
	v_pk_fma_f32 v[18:19], v[78:79], v[156:157], v[8:9] op_sel_hi:[1,0,1]
	v_add_f32_dpp v15, v24, v24 row_ror:8 row_mask:0xf bank_mask:0xf bound_ctrl:1
	s_nop 1
	v_add_f32_dpp v15, v15, v15 row_ror:4 row_mask:0xf bank_mask:0xf bound_ctrl:1
	s_nop 1
	v_add_f32_dpp v15, v15, v15 row_ror:2 row_mask:0xf bank_mask:0xf bound_ctrl:1
	s_nop 1
	v_add_f32_dpp v30, v15, v15 row_ror:1 row_mask:0xf bank_mask:0xf bound_ctrl:1
	s_waitcnt lgkmcnt(5)
	v_pk_fma_f32 v[10:11], v[80:81], v[30:31], v[16:17] op_sel_hi:[1,0,1] neg_lo:[0,1,0] neg_hi:[0,1,0]
	v_pk_fma_f32 v[8:9], v[82:83], v[30:31], v[18:19] op_sel_hi:[1,0,1] neg_lo:[0,1,0] neg_hi:[0,1,0]
	v_pk_mul_f32 v[24:25], v[10:11], v[84:85] op_sel:[0,0] op_sel_hi:[0,1]
	v_pk_fma_f32 v[24:25], v[10:11], v[86:87], v[24:25] op_sel:[1,0,0] op_sel_hi:[1,1,1]
	v_pk_fma_f32 v[24:25], v[8:9], v[88:89], v[24:25] op_sel:[0,0,0] op_sel_hi:[0,1,1]
	v_pk_fma_f32 v[24:25], v[8:9], v[90:91], v[24:25] op_sel:[1,0,0] op_sel_hi:[1,1,1]
	v_pk_fma_f32 v[16:17], v[92:93], v[156:157], v[10:11] op_sel:[0,1,0] op_sel_hi:[1,1,1]
	v_pk_fma_f32 v[18:19], v[94:95], v[156:157], v[8:9] op_sel:[0,1,0] op_sel_hi:[1,1,1]
	v_add_f32_dpp v15, v24, v24 row_ror:8 row_mask:0xf bank_mask:0xf bound_ctrl:1
	v_add_f32_dpp v32, v25, v25 row_ror:8 row_mask:0xf bank_mask:0xf bound_ctrl:1
	ds_read_b128 v[124:127], v34 offset:11264
	v_add_f32_dpp v15, v15, v15 row_ror:4 row_mask:0xf bank_mask:0xf bound_ctrl:1
	ds_read_b128 v[128:131], v34 offset:11520
	ds_read_b128 v[132:135], v34 offset:11776
	v_add_f32_dpp v15, v15, v15 row_ror:2 row_mask:0xf bank_mask:0xf bound_ctrl:1
	ds_read_b128 v[136:139], v34 offset:12032
	ds_read_b128 v[160:163], v35 offset:48
	v_add_f32_dpp v30, v15, v15 row_ror:1 row_mask:0xf bank_mask:0xf bound_ctrl:1
	s_waitcnt lgkmcnt(5)
	v_pk_fma_f32 v[10:11], v[96:97], v[30:31], v[16:17] op_sel_hi:[1,0,1] neg_lo:[0,1,0] neg_hi:[0,1,0]
	v_pk_fma_f32 v[8:9], v[98:99], v[30:31], v[18:19] op_sel_hi:[1,0,1] neg_lo:[0,1,0] neg_hi:[0,1,0]
	v_pk_mul_f32 v[24:25], v[10:11], v[100:101] op_sel:[0,0] op_sel_hi:[0,1]
	v_pk_fma_f32 v[24:25], v[10:11], v[102:103], v[24:25] op_sel:[1,0,0] op_sel_hi:[1,1,1]
	v_pk_fma_f32 v[24:25], v[8:9], v[104:105], v[24:25] op_sel:[0,0,0] op_sel_hi:[0,1,1]
	v_pk_fma_f32 v[24:25], v[8:9], v[106:107], v[24:25] op_sel:[1,0,0] op_sel_hi:[1,1,1]
	v_pk_fma_f32 v[16:17], v[108:109], v[158:159], v[10:11] op_sel_hi:[1,0,1]
	v_pk_fma_f32 v[18:19], v[110:111], v[158:159], v[8:9] op_sel_hi:[1,0,1]
	v_add_f32_dpp v15, v24, v24 row_ror:8 row_mask:0xf bank_mask:0xf bound_ctrl:1
	v_add_f32_dpp v33, v25, v25 row_ror:8 row_mask:0xf bank_mask:0xf bound_ctrl:1
	ds_read_b128 v[76:79], v34 offset:12288
	v_add_f32_dpp v15, v15, v15 row_ror:4 row_mask:0xf bank_mask:0xf bound_ctrl:1
	ds_read_b128 v[80:83], v34 offset:12544
	ds_read_b128 v[84:87], v34 offset:12800
	v_add_f32_dpp v15, v15, v15 row_ror:2 row_mask:0xf bank_mask:0xf bound_ctrl:1
	ds_read_b128 v[88:91], v34 offset:13056
	s_nop 0
	v_add_f32_dpp v30, v15, v15 row_ror:1 row_mask:0xf bank_mask:0xf bound_ctrl:1
	ds_write2st64_b32 v37, v32, v33 offset0:16 offset1:18
	s_waitcnt lgkmcnt(5)
	v_pk_fma_f32 v[10:11], v[112:113], v[30:31], v[16:17] op_sel_hi:[1,0,1] neg_lo:[0,1,0] neg_hi:[0,1,0]
	v_pk_fma_f32 v[8:9], v[114:115], v[30:31], v[18:19] op_sel_hi:[1,0,1] neg_lo:[0,1,0] neg_hi:[0,1,0]
	v_pk_mul_f32 v[24:25], v[10:11], v[116:117] op_sel:[0,0] op_sel_hi:[0,1]
	v_pk_fma_f32 v[24:25], v[10:11], v[118:119], v[24:25] op_sel:[1,0,0] op_sel_hi:[1,1,1]
	v_pk_fma_f32 v[24:25], v[8:9], v[120:121], v[24:25] op_sel:[0,0,0] op_sel_hi:[0,1,1]
	v_pk_fma_f32 v[24:25], v[8:9], v[122:123], v[24:25] op_sel:[1,0,0] op_sel_hi:[1,1,1]
	v_pk_fma_f32 v[16:17], v[124:125], v[158:159], v[10:11] op_sel:[0,1,0] op_sel_hi:[1,1,1]
	v_pk_fma_f32 v[18:19], v[126:127], v[158:159], v[8:9] op_sel:[0,1,0] op_sel_hi:[1,1,1]
	v_add_f32_dpp v15, v24, v24 row_ror:8 row_mask:0xf bank_mask:0xf bound_ctrl:1
	v_add_f32_dpp v32, v25, v25 row_ror:8 row_mask:0xf bank_mask:0xf bound_ctrl:1
	ds_read_b128 v[92:95], v34 offset:13312
	v_add_f32_dpp v15, v15, v15 row_ror:4 row_mask:0xf bank_mask:0xf bound_ctrl:1
	ds_read_b128 v[96:99], v34 offset:13568
	ds_read_b128 v[100:103], v34 offset:13824
	v_add_f32_dpp v15, v15, v15 row_ror:2 row_mask:0xf bank_mask:0xf bound_ctrl:1
	ds_read_b128 v[104:107], v34 offset:14080
	s_nop 0
	v_add_f32_dpp v30, v15, v15 row_ror:1 row_mask:0xf bank_mask:0xf bound_ctrl:1
	s_waitcnt lgkmcnt(4)
	v_pk_fma_f32 v[10:11], v[128:129], v[30:31], v[16:17] op_sel_hi:[1,0,1] neg_lo:[0,1,0] neg_hi:[0,1,0]
	v_pk_fma_f32 v[8:9], v[130:131], v[30:31], v[18:19] op_sel_hi:[1,0,1] neg_lo:[0,1,0] neg_hi:[0,1,0]
	v_pk_mul_f32 v[24:25], v[10:11], v[132:133] op_sel:[0,0] op_sel_hi:[0,1]
	v_pk_fma_f32 v[24:25], v[10:11], v[134:135], v[24:25] op_sel:[1,0,0] op_sel_hi:[1,1,1]
	v_pk_fma_f32 v[24:25], v[8:9], v[136:137], v[24:25] op_sel:[0,0,0] op_sel_hi:[0,1,1]
	v_pk_fma_f32 v[24:25], v[8:9], v[138:139], v[24:25] op_sel:[1,0,0] op_sel_hi:[1,1,1]
	v_pk_fma_f32 v[16:17], v[76:77], v[160:161], v[10:11] op_sel_hi:[1,0,1]
	v_pk_fma_f32 v[18:19], v[78:79], v[160:161], v[8:9] op_sel_hi:[1,0,1]
	v_add_f32_dpp v15, v24, v24 row_ror:8 row_mask:0xf bank_mask:0xf bound_ctrl:1
	v_add_f32_dpp v33, v25, v25 row_ror:8 row_mask:0xf bank_mask:0xf bound_ctrl:1
	ds_read_b128 v[108:111], v34 offset:14336
	v_add_f32_dpp v15, v15, v15 row_ror:4 row_mask:0xf bank_mask:0xf bound_ctrl:1
	ds_read_b128 v[112:115], v34 offset:14592
	ds_read_b128 v[116:119], v34 offset:14848
	v_add_f32_dpp v15, v15, v15 row_ror:2 row_mask:0xf bank_mask:0xf bound_ctrl:1
	ds_read_b128 v[120:123], v34 offset:15104
	ds_read_b128 v[140:143], v34 offset:34048
	v_add_f32_dpp v30, v15, v15 row_ror:1 row_mask:0xf bank_mask:0xf bound_ctrl:1
	ds_write2st64_b32 v37, v32, v33 offset0:20 offset1:22
	s_waitcnt lgkmcnt(6)
	v_pk_fma_f32 v[10:11], v[80:81], v[30:31], v[16:17] op_sel_hi:[1,0,1] neg_lo:[0,1,0] neg_hi:[0,1,0]
	v_pk_fma_f32 v[8:9], v[82:83], v[30:31], v[18:19] op_sel_hi:[1,0,1] neg_lo:[0,1,0] neg_hi:[0,1,0]
	v_pk_mul_f32 v[24:25], v[10:11], v[84:85] op_sel:[0,0] op_sel_hi:[0,1]
	v_pk_fma_f32 v[24:25], v[10:11], v[86:87], v[24:25] op_sel:[1,0,0] op_sel_hi:[1,1,1]
	v_pk_fma_f32 v[24:25], v[8:9], v[88:89], v[24:25] op_sel:[0,0,0] op_sel_hi:[0,1,1]
	v_pk_fma_f32 v[24:25], v[8:9], v[90:91], v[24:25] op_sel:[1,0,0] op_sel_hi:[1,1,1]
	v_pk_fma_f32 v[16:17], v[92:93], v[160:161], v[10:11] op_sel:[0,1,0] op_sel_hi:[1,1,1]
	v_pk_fma_f32 v[18:19], v[94:95], v[160:161], v[8:9] op_sel:[0,1,0] op_sel_hi:[1,1,1]
	v_add_f32_dpp v15, v24, v24 row_ror:8 row_mask:0xf bank_mask:0xf bound_ctrl:1
	v_add_f32_dpp v32, v25, v25 row_ror:8 row_mask:0xf bank_mask:0xf bound_ctrl:1
	ds_read_b128 v[124:127], v34 offset:15360
	v_add_f32_dpp v15, v15, v15 row_ror:4 row_mask:0xf bank_mask:0xf bound_ctrl:1
	ds_read_b128 v[128:131], v34 offset:15616
	ds_read_b128 v[132:135], v34 offset:15872
	v_add_f32_dpp v15, v15, v15 row_ror:2 row_mask:0xf bank_mask:0xf bound_ctrl:1
	ds_read_b128 v[136:139], v34 offset:16128
	ds_read_b128 v[156:159], v35 offset:64
	v_add_f32_dpp v30, v15, v15 row_ror:1 row_mask:0xf bank_mask:0xf bound_ctrl:1
	s_waitcnt lgkmcnt(5)
	v_pk_fma_f32 v[10:11], v[96:97], v[30:31], v[16:17] op_sel_hi:[1,0,1] neg_lo:[0,1,0] neg_hi:[0,1,0]
	v_pk_fma_f32 v[8:9], v[98:99], v[30:31], v[18:19] op_sel_hi:[1,0,1] neg_lo:[0,1,0] neg_hi:[0,1,0]
	v_pk_mul_f32 v[24:25], v[10:11], v[100:101] op_sel:[0,0] op_sel_hi:[0,1]
	v_pk_fma_f32 v[24:25], v[10:11], v[102:103], v[24:25] op_sel:[1,0,0] op_sel_hi:[1,1,1]
	v_pk_fma_f32 v[24:25], v[8:9], v[104:105], v[24:25] op_sel:[0,0,0] op_sel_hi:[0,1,1]
	v_pk_fma_f32 v[24:25], v[8:9], v[106:107], v[24:25] op_sel:[1,0,0] op_sel_hi:[1,1,1]
	v_pk_fma_f32 v[16:17], v[108:109], v[162:163], v[10:11] op_sel_hi:[1,0,1]
	v_pk_fma_f32 v[18:19], v[110:111], v[162:163], v[8:9] op_sel_hi:[1,0,1]
	v_add_f32_dpp v15, v24, v24 row_ror:8 row_mask:0xf bank_mask:0xf bound_ctrl:1
	v_add_f32_dpp v33, v25, v25 row_ror:8 row_mask:0xf bank_mask:0xf bound_ctrl:1
	ds_read_b128 v[76:79], v34 offset:16384
	v_add_f32_dpp v15, v15, v15 row_ror:4 row_mask:0xf bank_mask:0xf bound_ctrl:1
	ds_read_b128 v[80:83], v34 offset:16640
	ds_read_b128 v[84:87], v34 offset:16896
	v_add_f32_dpp v15, v15, v15 row_ror:2 row_mask:0xf bank_mask:0xf bound_ctrl:1
	ds_read_b128 v[88:91], v34 offset:17152
	ds_read_b128 v[144:147], v34 offset:33280
	v_add_f32_dpp v30, v15, v15 row_ror:1 row_mask:0xf bank_mask:0xf bound_ctrl:1
	ds_write2st64_b32 v37, v32, v33 offset0:24 offset1:26
	s_waitcnt lgkmcnt(6)
	v_pk_fma_f32 v[10:11], v[112:113], v[30:31], v[16:17] op_sel_hi:[1,0,1] neg_lo:[0,1,0] neg_hi:[0,1,0]
	v_pk_fma_f32 v[8:9], v[114:115], v[30:31], v[18:19] op_sel_hi:[1,0,1] neg_lo:[0,1,0] neg_hi:[0,1,0]
	v_pk_mul_f32 v[24:25], v[10:11], v[116:117] op_sel:[0,0] op_sel_hi:[0,1]
	v_pk_fma_f32 v[24:25], v[10:11], v[118:119], v[24:25] op_sel:[1,0,0] op_sel_hi:[1,1,1]
	v_pk_fma_f32 v[24:25], v[8:9], v[120:121], v[24:25] op_sel:[0,0,0] op_sel_hi:[0,1,1]
	v_pk_fma_f32 v[24:25], v[8:9], v[122:123], v[24:25] op_sel:[1,0,0] op_sel_hi:[1,1,1]
	v_pk_fma_f32 v[16:17], v[124:125], v[162:163], v[10:11] op_sel:[0,1,0] op_sel_hi:[1,1,1]
	v_pk_fma_f32 v[18:19], v[126:127], v[162:163], v[8:9] op_sel:[0,1,0] op_sel_hi:[1,1,1]
	v_add_f32_dpp v15, v24, v24 row_ror:8 row_mask:0xf bank_mask:0xf bound_ctrl:1
	v_add_f32_dpp v32, v25, v25 row_ror:8 row_mask:0xf bank_mask:0xf bound_ctrl:1
	ds_read_b128 v[92:95], v34 offset:17408
	v_add_f32_dpp v15, v15, v15 row_ror:4 row_mask:0xf bank_mask:0xf bound_ctrl:1
	ds_read_b128 v[96:99], v34 offset:17664
	ds_read_b128 v[100:103], v34 offset:17920
	v_add_f32_dpp v15, v15, v15 row_ror:2 row_mask:0xf bank_mask:0xf bound_ctrl:1
	ds_read_b128 v[104:107], v34 offset:18176
	s_nop 0
	v_add_f32_dpp v30, v15, v15 row_ror:1 row_mask:0xf bank_mask:0xf bound_ctrl:1
	s_waitcnt lgkmcnt(4)
	v_pk_fma_f32 v[10:11], v[128:129], v[30:31], v[16:17] op_sel_hi:[1,0,1] neg_lo:[0,1,0] neg_hi:[0,1,0]
	v_pk_fma_f32 v[8:9], v[130:131], v[30:31], v[18:19] op_sel_hi:[1,0,1] neg_lo:[0,1,0] neg_hi:[0,1,0]
	v_pk_mul_f32 v[24:25], v[10:11], v[132:133] op_sel:[0,0] op_sel_hi:[0,1]
	v_pk_fma_f32 v[24:25], v[10:11], v[134:135], v[24:25] op_sel:[1,0,0] op_sel_hi:[1,1,1]
	v_pk_fma_f32 v[24:25], v[8:9], v[136:137], v[24:25] op_sel:[0,0,0] op_sel_hi:[0,1,1]
	v_pk_fma_f32 v[24:25], v[8:9], v[138:139], v[24:25] op_sel:[1,0,0] op_sel_hi:[1,1,1]
	s_nop 1
	v_add_f32_dpp v33, v25, v25 row_ror:8 row_mask:0xf bank_mask:0xf bound_ctrl:1
	ds_read_b128 v[108:111], v34 offset:18432
	ds_read_b128 v[112:115], v34 offset:18688
	ds_read_b128 v[116:119], v34 offset:18944
	ds_read_b128 v[120:123], v34 offset:19200
	ds_write2st64_b32 v37, v32, v33 offset0:28 offset1:30
	v_pk_mul_f32 v[10:11], v[10:11], v[140:141]
	v_pk_mul_f32 v[8:9], v[8:9], v[142:143]
	v_pk_mul_f32 v[24:25], v[10:11], v[144:145]
	v_pk_fma_f32 v[24:25], v[8:9], v[146:147], v[24:25]
	v_add_f32_e32 v24, v24, v25
	v_pk_fma_f32 v[16:17], v[76:77], v[156:157], v[10:11] op_sel_hi:[1,0,1]
	v_pk_fma_f32 v[18:19], v[78:79], v[156:157], v[8:9] op_sel_hi:[1,0,1]
	v_add_f32_dpp v15, v24, v24 row_ror:8 row_mask:0xf bank_mask:0xf bound_ctrl:1
	s_nop 1
	v_add_f32_dpp v15, v15, v15 row_ror:4 row_mask:0xf bank_mask:0xf bound_ctrl:1
	s_nop 1
	v_add_f32_dpp v15, v15, v15 row_ror:2 row_mask:0xf bank_mask:0xf bound_ctrl:1
	s_nop 1
	v_add_f32_dpp v30, v15, v15 row_ror:1 row_mask:0xf bank_mask:0xf bound_ctrl:1
	s_waitcnt lgkmcnt(5)
	v_pk_fma_f32 v[10:11], v[80:81], v[30:31], v[16:17] op_sel_hi:[1,0,1] neg_lo:[0,1,0] neg_hi:[0,1,0]
	v_pk_fma_f32 v[8:9], v[82:83], v[30:31], v[18:19] op_sel_hi:[1,0,1] neg_lo:[0,1,0] neg_hi:[0,1,0]
	v_pk_mul_f32 v[24:25], v[10:11], v[84:85] op_sel:[0,0] op_sel_hi:[0,1]
	v_pk_fma_f32 v[24:25], v[10:11], v[86:87], v[24:25] op_sel:[1,0,0] op_sel_hi:[1,1,1]
	v_pk_fma_f32 v[24:25], v[8:9], v[88:89], v[24:25] op_sel:[0,0,0] op_sel_hi:[0,1,1]
	v_pk_fma_f32 v[24:25], v[8:9], v[90:91], v[24:25] op_sel:[1,0,0] op_sel_hi:[1,1,1]
	v_pk_fma_f32 v[16:17], v[92:93], v[156:157], v[10:11] op_sel:[0,1,0] op_sel_hi:[1,1,1]
	v_pk_fma_f32 v[18:19], v[94:95], v[156:157], v[8:9] op_sel:[0,1,0] op_sel_hi:[1,1,1]
	v_add_f32_dpp v15, v24, v24 row_ror:8 row_mask:0xf bank_mask:0xf bound_ctrl:1
	v_add_f32_dpp v32, v25, v25 row_ror:8 row_mask:0xf bank_mask:0xf bound_ctrl:1
	ds_read_b128 v[124:127], v34 offset:19456
	v_add_f32_dpp v15, v15, v15 row_ror:4 row_mask:0xf bank_mask:0xf bound_ctrl:1
	ds_read_b128 v[128:131], v34 offset:19712
	ds_read_b128 v[132:135], v34 offset:19968
	v_add_f32_dpp v15, v15, v15 row_ror:2 row_mask:0xf bank_mask:0xf bound_ctrl:1
	ds_read_b128 v[136:139], v34 offset:20224
	ds_read_b128 v[160:163], v35 offset:80
	v_add_f32_dpp v30, v15, v15 row_ror:1 row_mask:0xf bank_mask:0xf bound_ctrl:1
	s_waitcnt lgkmcnt(5)
	v_pk_fma_f32 v[10:11], v[96:97], v[30:31], v[16:17] op_sel_hi:[1,0,1] neg_lo:[0,1,0] neg_hi:[0,1,0]
	v_pk_fma_f32 v[8:9], v[98:99], v[30:31], v[18:19] op_sel_hi:[1,0,1] neg_lo:[0,1,0] neg_hi:[0,1,0]
	v_pk_mul_f32 v[24:25], v[10:11], v[100:101] op_sel:[0,0] op_sel_hi:[0,1]
	v_pk_fma_f32 v[24:25], v[10:11], v[102:103], v[24:25] op_sel:[1,0,0] op_sel_hi:[1,1,1]
	v_pk_fma_f32 v[24:25], v[8:9], v[104:105], v[24:25] op_sel:[0,0,0] op_sel_hi:[0,1,1]
	v_pk_fma_f32 v[24:25], v[8:9], v[106:107], v[24:25] op_sel:[1,0,0] op_sel_hi:[1,1,1]
	v_pk_fma_f32 v[16:17], v[108:109], v[158:159], v[10:11] op_sel_hi:[1,0,1]
	v_pk_fma_f32 v[18:19], v[110:111], v[158:159], v[8:9] op_sel_hi:[1,0,1]
	v_add_f32_dpp v15, v24, v24 row_ror:8 row_mask:0xf bank_mask:0xf bound_ctrl:1
	v_add_f32_dpp v33, v25, v25 row_ror:8 row_mask:0xf bank_mask:0xf bound_ctrl:1
	ds_read_b128 v[76:79], v34 offset:20480
	v_add_f32_dpp v15, v15, v15 row_ror:4 row_mask:0xf bank_mask:0xf bound_ctrl:1
	ds_read_b128 v[80:83], v34 offset:20736
	ds_read_b128 v[84:87], v34 offset:20992
	v_add_f32_dpp v15, v15, v15 row_ror:2 row_mask:0xf bank_mask:0xf bound_ctrl:1
	ds_read_b128 v[88:91], v34 offset:21248
	s_nop 0
	v_add_f32_dpp v30, v15, v15 row_ror:1 row_mask:0xf bank_mask:0xf bound_ctrl:1
	ds_write2st64_b32 v37, v32, v33 offset0:32 offset1:34
	s_waitcnt lgkmcnt(5)
	v_pk_fma_f32 v[10:11], v[112:113], v[30:31], v[16:17] op_sel_hi:[1,0,1] neg_lo:[0,1,0] neg_hi:[0,1,0]
	v_pk_fma_f32 v[8:9], v[114:115], v[30:31], v[18:19] op_sel_hi:[1,0,1] neg_lo:[0,1,0] neg_hi:[0,1,0]
	v_pk_mul_f32 v[24:25], v[10:11], v[116:117] op_sel:[0,0] op_sel_hi:[0,1]
	v_pk_fma_f32 v[24:25], v[10:11], v[118:119], v[24:25] op_sel:[1,0,0] op_sel_hi:[1,1,1]
	v_pk_fma_f32 v[24:25], v[8:9], v[120:121], v[24:25] op_sel:[0,0,0] op_sel_hi:[0,1,1]
	v_pk_fma_f32 v[24:25], v[8:9], v[122:123], v[24:25] op_sel:[1,0,0] op_sel_hi:[1,1,1]
	v_pk_fma_f32 v[16:17], v[124:125], v[158:159], v[10:11] op_sel:[0,1,0] op_sel_hi:[1,1,1]
	v_pk_fma_f32 v[18:19], v[126:127], v[158:159], v[8:9] op_sel:[0,1,0] op_sel_hi:[1,1,1]
	v_add_f32_dpp v15, v24, v24 row_ror:8 row_mask:0xf bank_mask:0xf bound_ctrl:1
	v_add_f32_dpp v32, v25, v25 row_ror:8 row_mask:0xf bank_mask:0xf bound_ctrl:1
	ds_read_b128 v[92:95], v34 offset:21504
	v_add_f32_dpp v15, v15, v15 row_ror:4 row_mask:0xf bank_mask:0xf bound_ctrl:1
	ds_read_b128 v[96:99], v34 offset:21760
	ds_read_b128 v[100:103], v34 offset:22016
	v_add_f32_dpp v15, v15, v15 row_ror:2 row_mask:0xf bank_mask:0xf bound_ctrl:1
	ds_read_b128 v[104:107], v34 offset:22272
	s_nop 0
	v_add_f32_dpp v30, v15, v15 row_ror:1 row_mask:0xf bank_mask:0xf bound_ctrl:1
	s_waitcnt lgkmcnt(4)
	v_pk_fma_f32 v[10:11], v[128:129], v[30:31], v[16:17] op_sel_hi:[1,0,1] neg_lo:[0,1,0] neg_hi:[0,1,0]
	v_pk_fma_f32 v[8:9], v[130:131], v[30:31], v[18:19] op_sel_hi:[1,0,1] neg_lo:[0,1,0] neg_hi:[0,1,0]
	v_pk_mul_f32 v[24:25], v[10:11], v[132:133] op_sel:[0,0] op_sel_hi:[0,1]
	v_pk_fma_f32 v[24:25], v[10:11], v[134:135], v[24:25] op_sel:[1,0,0] op_sel_hi:[1,1,1]
	v_pk_fma_f32 v[24:25], v[8:9], v[136:137], v[24:25] op_sel:[0,0,0] op_sel_hi:[0,1,1]
	v_pk_fma_f32 v[24:25], v[8:9], v[138:139], v[24:25] op_sel:[1,0,0] op_sel_hi:[1,1,1]
	v_pk_fma_f32 v[16:17], v[76:77], v[160:161], v[10:11] op_sel_hi:[1,0,1]
	v_pk_fma_f32 v[18:19], v[78:79], v[160:161], v[8:9] op_sel_hi:[1,0,1]
	v_add_f32_dpp v15, v24, v24 row_ror:8 row_mask:0xf bank_mask:0xf bound_ctrl:1
	v_add_f32_dpp v33, v25, v25 row_ror:8 row_mask:0xf bank_mask:0xf bound_ctrl:1
	ds_read_b128 v[108:111], v34 offset:22528
	v_add_f32_dpp v15, v15, v15 row_ror:4 row_mask:0xf bank_mask:0xf bound_ctrl:1
	ds_read_b128 v[112:115], v34 offset:22784
	ds_read_b128 v[116:119], v34 offset:23040
	v_add_f32_dpp v15, v15, v15 row_ror:2 row_mask:0xf bank_mask:0xf bound_ctrl:1
	ds_read_b128 v[120:123], v34 offset:23296
	ds_read_b128 v[140:143], v34 offset:34304
	v_add_f32_dpp v30, v15, v15 row_ror:1 row_mask:0xf bank_mask:0xf bound_ctrl:1
	ds_write2st64_b32 v37, v32, v33 offset0:36 offset1:38
	s_waitcnt lgkmcnt(6)
	v_pk_fma_f32 v[10:11], v[80:81], v[30:31], v[16:17] op_sel_hi:[1,0,1] neg_lo:[0,1,0] neg_hi:[0,1,0]
	v_pk_fma_f32 v[8:9], v[82:83], v[30:31], v[18:19] op_sel_hi:[1,0,1] neg_lo:[0,1,0] neg_hi:[0,1,0]
	v_pk_mul_f32 v[24:25], v[10:11], v[84:85] op_sel:[0,0] op_sel_hi:[0,1]
	v_pk_fma_f32 v[24:25], v[10:11], v[86:87], v[24:25] op_sel:[1,0,0] op_sel_hi:[1,1,1]
	v_pk_fma_f32 v[24:25], v[8:9], v[88:89], v[24:25] op_sel:[0,0,0] op_sel_hi:[0,1,1]
	v_pk_fma_f32 v[24:25], v[8:9], v[90:91], v[24:25] op_sel:[1,0,0] op_sel_hi:[1,1,1]
	v_pk_fma_f32 v[16:17], v[92:93], v[160:161], v[10:11] op_sel:[0,1,0] op_sel_hi:[1,1,1]
	v_pk_fma_f32 v[18:19], v[94:95], v[160:161], v[8:9] op_sel:[0,1,0] op_sel_hi:[1,1,1]
	v_add_f32_dpp v15, v24, v24 row_ror:8 row_mask:0xf bank_mask:0xf bound_ctrl:1
	v_add_f32_dpp v32, v25, v25 row_ror:8 row_mask:0xf bank_mask:0xf bound_ctrl:1
	ds_read_b128 v[124:127], v34 offset:23552
	v_add_f32_dpp v15, v15, v15 row_ror:4 row_mask:0xf bank_mask:0xf bound_ctrl:1
	ds_read_b128 v[128:131], v34 offset:23808
	ds_read_b128 v[132:135], v34 offset:24064
	v_add_f32_dpp v15, v15, v15 row_ror:2 row_mask:0xf bank_mask:0xf bound_ctrl:1
	ds_read_b128 v[136:139], v34 offset:24320
	ds_read_b128 v[156:159], v35 offset:96
	v_add_f32_dpp v30, v15, v15 row_ror:1 row_mask:0xf bank_mask:0xf bound_ctrl:1
	s_waitcnt lgkmcnt(5)
	v_pk_fma_f32 v[10:11], v[96:97], v[30:31], v[16:17] op_sel_hi:[1,0,1] neg_lo:[0,1,0] neg_hi:[0,1,0]
	v_pk_fma_f32 v[8:9], v[98:99], v[30:31], v[18:19] op_sel_hi:[1,0,1] neg_lo:[0,1,0] neg_hi:[0,1,0]
	v_pk_mul_f32 v[24:25], v[10:11], v[100:101] op_sel:[0,0] op_sel_hi:[0,1]
	v_pk_fma_f32 v[24:25], v[10:11], v[102:103], v[24:25] op_sel:[1,0,0] op_sel_hi:[1,1,1]
	v_pk_fma_f32 v[24:25], v[8:9], v[104:105], v[24:25] op_sel:[0,0,0] op_sel_hi:[0,1,1]
	v_pk_fma_f32 v[24:25], v[8:9], v[106:107], v[24:25] op_sel:[1,0,0] op_sel_hi:[1,1,1]
	v_pk_fma_f32 v[16:17], v[108:109], v[162:163], v[10:11] op_sel_hi:[1,0,1]
	v_pk_fma_f32 v[18:19], v[110:111], v[162:163], v[8:9] op_sel_hi:[1,0,1]
	v_add_f32_dpp v15, v24, v24 row_ror:8 row_mask:0xf bank_mask:0xf bound_ctrl:1
	v_add_f32_dpp v33, v25, v25 row_ror:8 row_mask:0xf bank_mask:0xf bound_ctrl:1
	ds_read_b128 v[76:79], v34 offset:24576
	v_add_f32_dpp v15, v15, v15 row_ror:4 row_mask:0xf bank_mask:0xf bound_ctrl:1
	ds_read_b128 v[80:83], v34 offset:24832
	ds_read_b128 v[84:87], v34 offset:25088
	v_add_f32_dpp v15, v15, v15 row_ror:2 row_mask:0xf bank_mask:0xf bound_ctrl:1
	ds_read_b128 v[88:91], v34 offset:25344
	ds_read_b128 v[144:147], v34 offset:33536
	v_add_f32_dpp v30, v15, v15 row_ror:1 row_mask:0xf bank_mask:0xf bound_ctrl:1
	ds_write2st64_b32 v37, v32, v33 offset0:40 offset1:42
	s_waitcnt lgkmcnt(6)
	v_pk_fma_f32 v[10:11], v[112:113], v[30:31], v[16:17] op_sel_hi:[1,0,1] neg_lo:[0,1,0] neg_hi:[0,1,0]
	v_pk_fma_f32 v[8:9], v[114:115], v[30:31], v[18:19] op_sel_hi:[1,0,1] neg_lo:[0,1,0] neg_hi:[0,1,0]
	v_pk_mul_f32 v[24:25], v[10:11], v[116:117] op_sel:[0,0] op_sel_hi:[0,1]
	v_pk_fma_f32 v[24:25], v[10:11], v[118:119], v[24:25] op_sel:[1,0,0] op_sel_hi:[1,1,1]
	v_pk_fma_f32 v[24:25], v[8:9], v[120:121], v[24:25] op_sel:[0,0,0] op_sel_hi:[0,1,1]
	v_pk_fma_f32 v[24:25], v[8:9], v[122:123], v[24:25] op_sel:[1,0,0] op_sel_hi:[1,1,1]
	v_pk_fma_f32 v[16:17], v[124:125], v[162:163], v[10:11] op_sel:[0,1,0] op_sel_hi:[1,1,1]
	v_pk_fma_f32 v[18:19], v[126:127], v[162:163], v[8:9] op_sel:[0,1,0] op_sel_hi:[1,1,1]
	v_add_f32_dpp v15, v24, v24 row_ror:8 row_mask:0xf bank_mask:0xf bound_ctrl:1
	v_add_f32_dpp v32, v25, v25 row_ror:8 row_mask:0xf bank_mask:0xf bound_ctrl:1
	ds_read_b128 v[92:95], v34 offset:25600
	v_add_f32_dpp v15, v15, v15 row_ror:4 row_mask:0xf bank_mask:0xf bound_ctrl:1
	ds_read_b128 v[96:99], v34 offset:25856
	ds_read_b128 v[100:103], v34 offset:26112
	v_add_f32_dpp v15, v15, v15 row_ror:2 row_mask:0xf bank_mask:0xf bound_ctrl:1
	ds_read_b128 v[104:107], v34 offset:26368
	s_nop 0
	v_add_f32_dpp v30, v15, v15 row_ror:1 row_mask:0xf bank_mask:0xf bound_ctrl:1
	s_waitcnt lgkmcnt(4)
	v_pk_fma_f32 v[10:11], v[128:129], v[30:31], v[16:17] op_sel_hi:[1,0,1] neg_lo:[0,1,0] neg_hi:[0,1,0]
	v_pk_fma_f32 v[8:9], v[130:131], v[30:31], v[18:19] op_sel_hi:[1,0,1] neg_lo:[0,1,0] neg_hi:[0,1,0]
	v_pk_mul_f32 v[24:25], v[10:11], v[132:133] op_sel:[0,0] op_sel_hi:[0,1]
	v_pk_fma_f32 v[24:25], v[10:11], v[134:135], v[24:25] op_sel:[1,0,0] op_sel_hi:[1,1,1]
	v_pk_fma_f32 v[24:25], v[8:9], v[136:137], v[24:25] op_sel:[0,0,0] op_sel_hi:[0,1,1]
	v_pk_fma_f32 v[24:25], v[8:9], v[138:139], v[24:25] op_sel:[1,0,0] op_sel_hi:[1,1,1]
	s_nop 1
	v_add_f32_dpp v33, v25, v25 row_ror:8 row_mask:0xf bank_mask:0xf bound_ctrl:1
	ds_read_b128 v[108:111], v34 offset:26624
	ds_read_b128 v[112:115], v34 offset:26880
	ds_read_b128 v[116:119], v34 offset:27136
	ds_read_b128 v[120:123], v34 offset:27392
	ds_write2st64_b32 v37, v32, v33 offset0:44 offset1:46
	v_pk_mul_f32 v[10:11], v[10:11], v[140:141]
	v_pk_mul_f32 v[8:9], v[8:9], v[142:143]
	v_pk_mul_f32 v[24:25], v[10:11], v[144:145]
	v_pk_fma_f32 v[24:25], v[8:9], v[146:147], v[24:25]
	v_add_f32_e32 v24, v24, v25
	v_pk_fma_f32 v[16:17], v[76:77], v[156:157], v[10:11] op_sel_hi:[1,0,1]
	v_pk_fma_f32 v[18:19], v[78:79], v[156:157], v[8:9] op_sel_hi:[1,0,1]
	v_add_f32_dpp v15, v24, v24 row_ror:8 row_mask:0xf bank_mask:0xf bound_ctrl:1
	s_nop 1
	v_add_f32_dpp v15, v15, v15 row_ror:4 row_mask:0xf bank_mask:0xf bound_ctrl:1
	s_nop 1
	v_add_f32_dpp v15, v15, v15 row_ror:2 row_mask:0xf bank_mask:0xf bound_ctrl:1
	s_nop 1
	v_add_f32_dpp v30, v15, v15 row_ror:1 row_mask:0xf bank_mask:0xf bound_ctrl:1
	s_waitcnt lgkmcnt(5)
	v_pk_fma_f32 v[10:11], v[80:81], v[30:31], v[16:17] op_sel_hi:[1,0,1] neg_lo:[0,1,0] neg_hi:[0,1,0]
	v_pk_fma_f32 v[8:9], v[82:83], v[30:31], v[18:19] op_sel_hi:[1,0,1] neg_lo:[0,1,0] neg_hi:[0,1,0]
	v_pk_mul_f32 v[24:25], v[10:11], v[84:85] op_sel:[0,0] op_sel_hi:[0,1]
	v_pk_fma_f32 v[24:25], v[10:11], v[86:87], v[24:25] op_sel:[1,0,0] op_sel_hi:[1,1,1]
	v_pk_fma_f32 v[24:25], v[8:9], v[88:89], v[24:25] op_sel:[0,0,0] op_sel_hi:[0,1,1]
	v_pk_fma_f32 v[24:25], v[8:9], v[90:91], v[24:25] op_sel:[1,0,0] op_sel_hi:[1,1,1]
	v_pk_fma_f32 v[16:17], v[92:93], v[156:157], v[10:11] op_sel:[0,1,0] op_sel_hi:[1,1,1]
	v_pk_fma_f32 v[18:19], v[94:95], v[156:157], v[8:9] op_sel:[0,1,0] op_sel_hi:[1,1,1]
	v_add_f32_dpp v15, v24, v24 row_ror:8 row_mask:0xf bank_mask:0xf bound_ctrl:1
	v_add_f32_dpp v32, v25, v25 row_ror:8 row_mask:0xf bank_mask:0xf bound_ctrl:1
	ds_read_b128 v[124:127], v34 offset:27648
	v_add_f32_dpp v15, v15, v15 row_ror:4 row_mask:0xf bank_mask:0xf bound_ctrl:1
	ds_read_b128 v[128:131], v34 offset:27904
	ds_read_b128 v[132:135], v34 offset:28160
	v_add_f32_dpp v15, v15, v15 row_ror:2 row_mask:0xf bank_mask:0xf bound_ctrl:1
	ds_read_b128 v[136:139], v34 offset:28416
	ds_read_b128 v[160:163], v35 offset:112
	v_add_f32_dpp v30, v15, v15 row_ror:1 row_mask:0xf bank_mask:0xf bound_ctrl:1
	s_waitcnt lgkmcnt(5)
	v_pk_fma_f32 v[10:11], v[96:97], v[30:31], v[16:17] op_sel_hi:[1,0,1] neg_lo:[0,1,0] neg_hi:[0,1,0]
	v_pk_fma_f32 v[8:9], v[98:99], v[30:31], v[18:19] op_sel_hi:[1,0,1] neg_lo:[0,1,0] neg_hi:[0,1,0]
	v_pk_mul_f32 v[24:25], v[10:11], v[100:101] op_sel:[0,0] op_sel_hi:[0,1]
	v_pk_fma_f32 v[24:25], v[10:11], v[102:103], v[24:25] op_sel:[1,0,0] op_sel_hi:[1,1,1]
	v_pk_fma_f32 v[24:25], v[8:9], v[104:105], v[24:25] op_sel:[0,0,0] op_sel_hi:[0,1,1]
	v_pk_fma_f32 v[24:25], v[8:9], v[106:107], v[24:25] op_sel:[1,0,0] op_sel_hi:[1,1,1]
	v_pk_fma_f32 v[16:17], v[108:109], v[158:159], v[10:11] op_sel_hi:[1,0,1]
	v_pk_fma_f32 v[18:19], v[110:111], v[158:159], v[8:9] op_sel_hi:[1,0,1]
	v_add_f32_dpp v15, v24, v24 row_ror:8 row_mask:0xf bank_mask:0xf bound_ctrl:1
	v_add_f32_dpp v33, v25, v25 row_ror:8 row_mask:0xf bank_mask:0xf bound_ctrl:1
	ds_read_b128 v[76:79], v34 offset:28672
	v_add_f32_dpp v15, v15, v15 row_ror:4 row_mask:0xf bank_mask:0xf bound_ctrl:1
	ds_read_b128 v[80:83], v34 offset:28928
	ds_read_b128 v[84:87], v34 offset:29184
	v_add_f32_dpp v15, v15, v15 row_ror:2 row_mask:0xf bank_mask:0xf bound_ctrl:1
	ds_read_b128 v[88:91], v34 offset:29440
	s_nop 0
	v_add_f32_dpp v30, v15, v15 row_ror:1 row_mask:0xf bank_mask:0xf bound_ctrl:1
	ds_write2st64_b32 v37, v32, v33 offset0:48 offset1:50
	ds_read_b128 v[56:59], v52
	s_waitcnt lgkmcnt(5)
	v_pk_fma_f32 v[10:11], v[112:113], v[30:31], v[16:17] op_sel_hi:[1,0,1] neg_lo:[0,1,0] neg_hi:[0,1,0]
	v_pk_fma_f32 v[8:9], v[114:115], v[30:31], v[18:19] op_sel_hi:[1,0,1] neg_lo:[0,1,0] neg_hi:[0,1,0]
	v_pk_mul_f32 v[24:25], v[10:11], v[116:117] op_sel:[0,0] op_sel_hi:[0,1]
	v_pk_fma_f32 v[24:25], v[10:11], v[118:119], v[24:25] op_sel:[1,0,0] op_sel_hi:[1,1,1]
	v_pk_fma_f32 v[24:25], v[8:9], v[120:121], v[24:25] op_sel:[0,0,0] op_sel_hi:[0,1,1]
	v_pk_fma_f32 v[24:25], v[8:9], v[122:123], v[24:25] op_sel:[1,0,0] op_sel_hi:[1,1,1]
	v_pk_fma_f32 v[16:17], v[124:125], v[158:159], v[10:11] op_sel:[0,1,0] op_sel_hi:[1,1,1]
	v_pk_fma_f32 v[18:19], v[126:127], v[158:159], v[8:9] op_sel:[0,1,0] op_sel_hi:[1,1,1]
	v_add_f32_dpp v15, v24, v24 row_ror:8 row_mask:0xf bank_mask:0xf bound_ctrl:1
	v_add_f32_dpp v32, v25, v25 row_ror:8 row_mask:0xf bank_mask:0xf bound_ctrl:1
	ds_read_b128 v[92:95], v34 offset:29696
	v_add_f32_dpp v15, v15, v15 row_ror:4 row_mask:0xf bank_mask:0xf bound_ctrl:1
	ds_read_b128 v[96:99], v34 offset:29952
	ds_read_b128 v[100:103], v34 offset:30208
	v_add_f32_dpp v15, v15, v15 row_ror:2 row_mask:0xf bank_mask:0xf bound_ctrl:1
	ds_read_b128 v[104:107], v34 offset:30464
	s_nop 0
	v_add_f32_dpp v30, v15, v15 row_ror:1 row_mask:0xf bank_mask:0xf bound_ctrl:1
	s_waitcnt lgkmcnt(4)
	v_min_u32_e32 v56, v56, v57
	v_min3_u32 v56, v56, v58, v59
	v_pk_fma_f32 v[10:11], v[128:129], v[30:31], v[16:17] op_sel_hi:[1,0,1] neg_lo:[0,1,0] neg_hi:[0,1,0]
	v_pk_fma_f32 v[8:9], v[130:131], v[30:31], v[18:19] op_sel_hi:[1,0,1] neg_lo:[0,1,0] neg_hi:[0,1,0]
	v_pk_mul_f32 v[24:25], v[10:11], v[132:133] op_sel:[0,0] op_sel_hi:[0,1]
	v_pk_fma_f32 v[24:25], v[10:11], v[134:135], v[24:25] op_sel:[1,0,0] op_sel_hi:[1,1,1]
	v_pk_fma_f32 v[24:25], v[8:9], v[136:137], v[24:25] op_sel:[0,0,0] op_sel_hi:[0,1,1]
	v_pk_fma_f32 v[24:25], v[8:9], v[138:139], v[24:25] op_sel:[1,0,0] op_sel_hi:[1,1,1]
	v_pk_fma_f32 v[16:17], v[76:77], v[160:161], v[10:11] op_sel_hi:[1,0,1]
	v_pk_fma_f32 v[18:19], v[78:79], v[160:161], v[8:9] op_sel_hi:[1,0,1]
	v_add_f32_dpp v15, v24, v24 row_ror:8 row_mask:0xf bank_mask:0xf bound_ctrl:1
	v_add_f32_dpp v33, v25, v25 row_ror:8 row_mask:0xf bank_mask:0xf bound_ctrl:1
	ds_read_b128 v[108:111], v34 offset:30720
	v_add_f32_dpp v15, v15, v15 row_ror:4 row_mask:0xf bank_mask:0xf bound_ctrl:1
	ds_read_b128 v[112:115], v34 offset:30976
	ds_read_b128 v[116:119], v34 offset:31232
	v_add_f32_dpp v15, v15, v15 row_ror:2 row_mask:0xf bank_mask:0xf bound_ctrl:1
	ds_read_b128 v[120:123], v34 offset:31488
	ds_read_b128 v[140:143], v34 offset:34560
	v_add_f32_dpp v30, v15, v15 row_ror:1 row_mask:0xf bank_mask:0xf bound_ctrl:1
	ds_write2st64_b32 v37, v32, v33 offset0:52 offset1:54
	s_waitcnt lgkmcnt(6)
	v_pk_fma_f32 v[10:11], v[80:81], v[30:31], v[16:17] op_sel_hi:[1,0,1] neg_lo:[0,1,0] neg_hi:[0,1,0]
	v_pk_fma_f32 v[8:9], v[82:83], v[30:31], v[18:19] op_sel_hi:[1,0,1] neg_lo:[0,1,0] neg_hi:[0,1,0]
	v_pk_mul_f32 v[24:25], v[10:11], v[84:85] op_sel:[0,0] op_sel_hi:[0,1]
	v_pk_fma_f32 v[24:25], v[10:11], v[86:87], v[24:25] op_sel:[1,0,0] op_sel_hi:[1,1,1]
	v_pk_fma_f32 v[24:25], v[8:9], v[88:89], v[24:25] op_sel:[0,0,0] op_sel_hi:[0,1,1]
	v_pk_fma_f32 v[24:25], v[8:9], v[90:91], v[24:25] op_sel:[1,0,0] op_sel_hi:[1,1,1]
	v_pk_fma_f32 v[16:17], v[92:93], v[160:161], v[10:11] op_sel:[0,1,0] op_sel_hi:[1,1,1]
	v_pk_fma_f32 v[18:19], v[94:95], v[160:161], v[8:9] op_sel:[0,1,0] op_sel_hi:[1,1,1]
	v_add_f32_dpp v15, v24, v24 row_ror:8 row_mask:0xf bank_mask:0xf bound_ctrl:1
	v_add_f32_dpp v32, v25, v25 row_ror:8 row_mask:0xf bank_mask:0xf bound_ctrl:1
	ds_read_b128 v[124:127], v34 offset:31744
	v_add_f32_dpp v15, v15, v15 row_ror:4 row_mask:0xf bank_mask:0xf bound_ctrl:1
	ds_read_b128 v[128:131], v34 offset:32000
	ds_read_b128 v[132:135], v34 offset:32256
	v_add_f32_dpp v15, v15, v15 row_ror:2 row_mask:0xf bank_mask:0xf bound_ctrl:1
	ds_read_b128 v[136:139], v34 offset:32512
	s_nop 0
	v_add_f32_dpp v30, v15, v15 row_ror:1 row_mask:0xf bank_mask:0xf bound_ctrl:1
	v_readfirstlane_b32 s54, v56
	s_add_u32 s64, s6, 2
	s_cmp_lt_u32 s54, s64
	s_cbranch_scc1 .Lss_spin_0
.Lss_ok_0:
	s_waitcnt lgkmcnt(4)
	v_pk_fma_f32 v[10:11], v[96:97], v[30:31], v[16:17] op_sel_hi:[1,0,1] neg_lo:[0,1,0] neg_hi:[0,1,0]
	v_pk_fma_f32 v[8:9], v[98:99], v[30:31], v[18:19] op_sel_hi:[1,0,1] neg_lo:[0,1,0] neg_hi:[0,1,0]
	v_pk_mul_f32 v[24:25], v[10:11], v[100:101] op_sel:[0,0] op_sel_hi:[0,1]
	v_pk_fma_f32 v[24:25], v[10:11], v[102:103], v[24:25] op_sel:[1,0,0] op_sel_hi:[1,1,1]
	v_pk_fma_f32 v[24:25], v[8:9], v[104:105], v[24:25] op_sel:[0,0,0] op_sel_hi:[0,1,1]
	v_pk_fma_f32 v[24:25], v[8:9], v[106:107], v[24:25] op_sel:[1,0,0] op_sel_hi:[1,1,1]
	v_pk_fma_f32 v[16:17], v[108:109], v[162:163], v[10:11] op_sel_hi:[1,0,1]
	v_pk_fma_f32 v[18:19], v[110:111], v[162:163], v[8:9] op_sel_hi:[1,0,1]
	v_add_f32_dpp v15, v24, v24 row_ror:8 row_mask:0xf bank_mask:0xf bound_ctrl:1
	v_add_f32_dpp v33, v25, v25 row_ror:8 row_mask:0xf bank_mask:0xf bound_ctrl:1
	ds_read_b128 v[76:79], v48 offset:0
	v_add_f32_dpp v15, v15, v15 row_ror:4 row_mask:0xf bank_mask:0xf bound_ctrl:1
	ds_read_b128 v[80:83], v48 offset:256
	ds_read_b128 v[84:87], v48 offset:512
	v_add_f32_dpp v15, v15, v15 row_ror:2 row_mask:0xf bank_mask:0xf bound_ctrl:1
	ds_read_b128 v[88:91], v48 offset:768
	ds_read_b128 v[144:147], v48 offset:32768
	v_add_f32_dpp v30, v15, v15 row_ror:1 row_mask:0xf bank_mask:0xf bound_ctrl:1
	ds_write2st64_b32 v37, v32, v33 offset0:56 offset1:58
	ds_read_b128 v[156:159], v49 offset:0
	s_waitcnt lgkmcnt(7)
	v_pk_fma_f32 v[10:11], v[112:113], v[30:31], v[16:17] op_sel_hi:[1,0,1] neg_lo:[0,1,0] neg_hi:[0,1,0]
	v_pk_fma_f32 v[8:9], v[114:115], v[30:31], v[18:19] op_sel_hi:[1,0,1] neg_lo:[0,1,0] neg_hi:[0,1,0]
	v_pk_mul_f32 v[24:25], v[10:11], v[116:117] op_sel:[0,0] op_sel_hi:[0,1]
	v_pk_fma_f32 v[24:25], v[10:11], v[118:119], v[24:25] op_sel:[1,0,0] op_sel_hi:[1,1,1]
	v_pk_fma_f32 v[24:25], v[8:9], v[120:121], v[24:25] op_sel:[0,0,0] op_sel_hi:[0,1,1]
	v_pk_fma_f32 v[24:25], v[8:9], v[122:123], v[24:25] op_sel:[1,0,0] op_sel_hi:[1,1,1]
	v_pk_fma_f32 v[16:17], v[124:125], v[162:163], v[10:11] op_sel:[0,1,0] op_sel_hi:[1,1,1]
	v_pk_fma_f32 v[18:19], v[126:127], v[162:163], v[8:9] op_sel:[0,1,0] op_sel_hi:[1,1,1]
	v_add_f32_dpp v15, v24, v24 row_ror:8 row_mask:0xf bank_mask:0xf bound_ctrl:1
	v_add_f32_dpp v32, v25, v25 row_ror:8 row_mask:0xf bank_mask:0xf bound_ctrl:1
	ds_read_b128 v[92:95], v48 offset:1024
	v_add_f32_dpp v15, v15, v15 row_ror:4 row_mask:0xf bank_mask:0xf bound_ctrl:1
	ds_read_b128 v[96:99], v48 offset:1280
	ds_read_b128 v[100:103], v48 offset:1536
	v_add_f32_dpp v15, v15, v15 row_ror:2 row_mask:0xf bank_mask:0xf bound_ctrl:1
	ds_read_b128 v[104:107], v48 offset:1792
	s_nop 0
	v_add_f32_dpp v30, v15, v15 row_ror:1 row_mask:0xf bank_mask:0xf bound_ctrl:1
	s_waitcnt lgkmcnt(4)
	v_pk_fma_f32 v[10:11], v[128:129], v[30:31], v[16:17] op_sel_hi:[1,0,1] neg_lo:[0,1,0] neg_hi:[0,1,0]
	v_pk_fma_f32 v[8:9], v[130:131], v[30:31], v[18:19] op_sel_hi:[1,0,1] neg_lo:[0,1,0] neg_hi:[0,1,0]
	v_pk_mul_f32 v[24:25], v[10:11], v[132:133] op_sel:[0,0] op_sel_hi:[0,1]
	v_pk_fma_f32 v[24:25], v[10:11], v[134:135], v[24:25] op_sel:[1,0,0] op_sel_hi:[1,1,1]
	v_pk_fma_f32 v[24:25], v[8:9], v[136:137], v[24:25] op_sel:[0,0,0] op_sel_hi:[0,1,1]
	v_pk_fma_f32 v[24:25], v[8:9], v[138:139], v[24:25] op_sel:[1,0,0] op_sel_hi:[1,1,1]
	s_nop 1
	v_add_f32_dpp v33, v25, v25 row_ror:8 row_mask:0xf bank_mask:0xf bound_ctrl:1
	ds_read_b128 v[108:111], v48 offset:2048
	ds_read_b128 v[112:115], v48 offset:2304
	ds_read_b128 v[116:119], v48 offset:2560
	ds_read_b128 v[120:123], v48 offset:2816
	ds_write2st64_b32 v37, v32, v33 offset0:60 offset1:62
	v_pk_mul_f32 v[10:11], v[10:11], v[140:141]
	v_pk_mul_f32 v[8:9], v[8:9], v[142:143]
	v_pk_mul_f32 v[24:25], v[10:11], v[144:145]
	v_pk_fma_f32 v[24:25], v[8:9], v[146:147], v[24:25]
	v_add_f32_e32 v24, v24, v25
	v_pk_fma_f32 v[16:17], v[76:77], v[156:157], v[10:11] op_sel_hi:[1,0,1]
	v_pk_fma_f32 v[18:19], v[78:79], v[156:157], v[8:9] op_sel_hi:[1,0,1]
	v_add_f32_dpp v15, v24, v24 row_ror:8 row_mask:0xf bank_mask:0xf bound_ctrl:1
	v_add_u32_e32 v51, 1, v51
	s_add_u32 s6, s6, 1
	v_add_f32_dpp v15, v15, v15 row_ror:4 row_mask:0xf bank_mask:0xf bound_ctrl:1
	ds_write_b32 v53, v51
	s_nop 0
	v_add_f32_dpp v15, v15, v15 row_ror:2 row_mask:0xf bank_mask:0xf bound_ctrl:1
	s_nop 1
	v_add_f32_dpp v30, v15, v15 row_ror:1 row_mask:0xf bank_mask:0xf bound_ctrl:1
	s_waitcnt lgkmcnt(6)
	v_pk_fma_f32 v[10:11], v[80:81], v[30:31], v[16:17] op_sel_hi:[1,0,1] neg_lo:[0,1,0] neg_hi:[0,1,0]
	v_pk_fma_f32 v[8:9], v[82:83], v[30:31], v[18:19] op_sel_hi:[1,0,1] neg_lo:[0,1,0] neg_hi:[0,1,0]
	v_pk_mul_f32 v[24:25], v[10:11], v[84:85] op_sel:[0,0] op_sel_hi:[0,1]
	v_pk_fma_f32 v[24:25], v[10:11], v[86:87], v[24:25] op_sel:[1,0,0] op_sel_hi:[1,1,1]
	v_pk_fma_f32 v[24:25], v[8:9], v[88:89], v[24:25] op_sel:[0,0,0] op_sel_hi:[0,1,1]
	v_pk_fma_f32 v[24:25], v[8:9], v[90:91], v[24:25] op_sel:[1,0,0] op_sel_hi:[1,1,1]
	v_pk_fma_f32 v[16:17], v[92:93], v[156:157], v[10:11] op_sel:[0,1,0] op_sel_hi:[1,1,1]
	v_pk_fma_f32 v[18:19], v[94:95], v[156:157], v[8:9] op_sel:[0,1,0] op_sel_hi:[1,1,1]
	v_add_f32_dpp v15, v24, v24 row_ror:8 row_mask:0xf bank_mask:0xf bound_ctrl:1
	v_add_f32_dpp v32, v25, v25 row_ror:8 row_mask:0xf bank_mask:0xf bound_ctrl:1
	ds_read_b128 v[124:127], v48 offset:3072
	v_add_f32_dpp v15, v15, v15 row_ror:4 row_mask:0xf bank_mask:0xf bound_ctrl:1
	ds_read_b128 v[128:131], v48 offset:3328
	ds_read_b128 v[132:135], v48 offset:3584
	v_add_f32_dpp v15, v15, v15 row_ror:2 row_mask:0xf bank_mask:0xf bound_ctrl:1
	ds_read_b128 v[136:139], v48 offset:3840
	ds_read_b128 v[160:163], v49 offset:16
	v_add_f32_dpp v30, v15, v15 row_ror:1 row_mask:0xf bank_mask:0xf bound_ctrl:1
	s_waitcnt lgkmcnt(5)
	v_pk_fma_f32 v[10:11], v[96:97], v[30:31], v[16:17] op_sel_hi:[1,0,1] neg_lo:[0,1,0] neg_hi:[0,1,0]
	v_pk_fma_f32 v[8:9], v[98:99], v[30:31], v[18:19] op_sel_hi:[1,0,1] neg_lo:[0,1,0] neg_hi:[0,1,0]
	v_pk_mul_f32 v[24:25], v[10:11], v[100:101] op_sel:[0,0] op_sel_hi:[0,1]
	v_pk_fma_f32 v[24:25], v[10:11], v[102:103], v[24:25] op_sel:[1,0,0] op_sel_hi:[1,1,1]
	v_pk_fma_f32 v[24:25], v[8:9], v[104:105], v[24:25] op_sel:[0,0,0] op_sel_hi:[0,1,1]
	v_pk_fma_f32 v[24:25], v[8:9], v[106:107], v[24:25] op_sel:[1,0,0] op_sel_hi:[1,1,1]
	v_pk_fma_f32 v[16:17], v[108:109], v[158:159], v[10:11] op_sel_hi:[1,0,1]
	v_pk_fma_f32 v[18:19], v[110:111], v[158:159], v[8:9] op_sel_hi:[1,0,1]
	v_add_f32_dpp v15, v24, v24 row_ror:8 row_mask:0xf bank_mask:0xf bound_ctrl:1
	v_add_f32_dpp v33, v25, v25 row_ror:8 row_mask:0xf bank_mask:0xf bound_ctrl:1
	ds_read_b128 v[76:79], v48 offset:4096
	v_add_f32_dpp v15, v15, v15 row_ror:4 row_mask:0xf bank_mask:0xf bound_ctrl:1
	ds_read_b128 v[80:83], v48 offset:4352
	ds_read_b128 v[84:87], v48 offset:4608
	v_add_f32_dpp v15, v15, v15 row_ror:2 row_mask:0xf bank_mask:0xf bound_ctrl:1
	ds_read_b128 v[88:91], v48 offset:4864
	s_nop 0
	v_add_f32_dpp v30, v15, v15 row_ror:1 row_mask:0xf bank_mask:0xf bound_ctrl:1
	ds_write2st64_b32 v50, v32, v33 offset0:0 offset1:2
	s_waitcnt lgkmcnt(5)
	v_pk_fma_f32 v[10:11], v[112:113], v[30:31], v[16:17] op_sel_hi:[1,0,1] neg_lo:[0,1,0] neg_hi:[0,1,0]
	v_pk_fma_f32 v[8:9], v[114:115], v[30:31], v[18:19] op_sel_hi:[1,0,1] neg_lo:[0,1,0] neg_hi:[0,1,0]
	v_pk_mul_f32 v[24:25], v[10:11], v[116:117] op_sel:[0,0] op_sel_hi:[0,1]
	v_pk_fma_f32 v[24:25], v[10:11], v[118:119], v[24:25] op_sel:[1,0,0] op_sel_hi:[1,1,1]
	v_pk_fma_f32 v[24:25], v[8:9], v[120:121], v[24:25] op_sel:[0,0,0] op_sel_hi:[0,1,1]
	v_pk_fma_f32 v[24:25], v[8:9], v[122:123], v[24:25] op_sel:[1,0,0] op_sel_hi:[1,1,1]
	v_pk_fma_f32 v[16:17], v[124:125], v[158:159], v[10:11] op_sel:[0,1,0] op_sel_hi:[1,1,1]
	v_pk_fma_f32 v[18:19], v[126:127], v[158:159], v[8:9] op_sel:[0,1,0] op_sel_hi:[1,1,1]
	v_add_f32_dpp v15, v24, v24 row_ror:8 row_mask:0xf bank_mask:0xf bound_ctrl:1
	v_add_f32_dpp v32, v25, v25 row_ror:8 row_mask:0xf bank_mask:0xf bound_ctrl:1
	ds_read_b128 v[92:95], v48 offset:5120
	v_add_f32_dpp v15, v15, v15 row_ror:4 row_mask:0xf bank_mask:0xf bound_ctrl:1
	ds_read_b128 v[96:99], v48 offset:5376
	ds_read_b128 v[100:103], v48 offset:5632
	v_add_f32_dpp v15, v15, v15 row_ror:2 row_mask:0xf bank_mask:0xf bound_ctrl:1
	ds_read_b128 v[104:107], v48 offset:5888
	s_nop 0
	v_add_f32_dpp v30, v15, v15 row_ror:1 row_mask:0xf bank_mask:0xf bound_ctrl:1
	s_waitcnt lgkmcnt(4)
	v_pk_fma_f32 v[10:11], v[128:129], v[30:31], v[16:17] op_sel_hi:[1,0,1] neg_lo:[0,1,0] neg_hi:[0,1,0]
	v_pk_fma_f32 v[8:9], v[130:131], v[30:31], v[18:19] op_sel_hi:[1,0,1] neg_lo:[0,1,0] neg_hi:[0,1,0]
	v_pk_mul_f32 v[24:25], v[10:11], v[132:133] op_sel:[0,0] op_sel_hi:[0,1]
	v_pk_fma_f32 v[24:25], v[10:11], v[134:135], v[24:25] op_sel:[1,0,0] op_sel_hi:[1,1,1]
	v_pk_fma_f32 v[24:25], v[8:9], v[136:137], v[24:25] op_sel:[0,0,0] op_sel_hi:[0,1,1]
	v_pk_fma_f32 v[24:25], v[8:9], v[138:139], v[24:25] op_sel:[1,0,0] op_sel_hi:[1,1,1]
	v_pk_fma_f32 v[16:17], v[76:77], v[160:161], v[10:11] op_sel_hi:[1,0,1]
	v_pk_fma_f32 v[18:19], v[78:79], v[160:161], v[8:9] op_sel_hi:[1,0,1]
	v_add_f32_dpp v15, v24, v24 row_ror:8 row_mask:0xf bank_mask:0xf bound_ctrl:1
	v_add_f32_dpp v33, v25, v25 row_ror:8 row_mask:0xf bank_mask:0xf bound_ctrl:1
	ds_read_b128 v[108:111], v48 offset:6144
	v_add_f32_dpp v15, v15, v15 row_ror:4 row_mask:0xf bank_mask:0xf bound_ctrl:1
	ds_read_b128 v[112:115], v48 offset:6400
	ds_read_b128 v[116:119], v48 offset:6656
	v_add_f32_dpp v15, v15, v15 row_ror:2 row_mask:0xf bank_mask:0xf bound_ctrl:1
	ds_read_b128 v[120:123], v48 offset:6912
	ds_read_b128 v[140:143], v48 offset:33792
	v_add_f32_dpp v30, v15, v15 row_ror:1 row_mask:0xf bank_mask:0xf bound_ctrl:1
	ds_write2st64_b32 v50, v32, v33 offset0:4 offset1:6
	s_waitcnt lgkmcnt(6)
	v_pk_fma_f32 v[10:11], v[80:81], v[30:31], v[16:17] op_sel_hi:[1,0,1] neg_lo:[0,1,0] neg_hi:[0,1,0]
	v_pk_fma_f32 v[8:9], v[82:83], v[30:31], v[18:19] op_sel_hi:[1,0,1] neg_lo:[0,1,0] neg_hi:[0,1,0]
	v_pk_mul_f32 v[24:25], v[10:11], v[84:85] op_sel:[0,0] op_sel_hi:[0,1]
	v_pk_fma_f32 v[24:25], v[10:11], v[86:87], v[24:25] op_sel:[1,0,0] op_sel_hi:[1,1,1]
	v_pk_fma_f32 v[24:25], v[8:9], v[88:89], v[24:25] op_sel:[0,0,0] op_sel_hi:[0,1,1]
	v_pk_fma_f32 v[24:25], v[8:9], v[90:91], v[24:25] op_sel:[1,0,0] op_sel_hi:[1,1,1]
	v_pk_fma_f32 v[16:17], v[92:93], v[160:161], v[10:11] op_sel:[0,1,0] op_sel_hi:[1,1,1]
	v_pk_fma_f32 v[18:19], v[94:95], v[160:161], v[8:9] op_sel:[0,1,0] op_sel_hi:[1,1,1]
	v_add_f32_dpp v15, v24, v24 row_ror:8 row_mask:0xf bank_mask:0xf bound_ctrl:1
	v_add_f32_dpp v32, v25, v25 row_ror:8 row_mask:0xf bank_mask:0xf bound_ctrl:1
	ds_read_b128 v[124:127], v48 offset:7168
	v_add_f32_dpp v15, v15, v15 row_ror:4 row_mask:0xf bank_mask:0xf bound_ctrl:1
	ds_read_b128 v[128:131], v48 offset:7424
	ds_read_b128 v[132:135], v48 offset:7680
	v_add_f32_dpp v15, v15, v15 row_ror:2 row_mask:0xf bank_mask:0xf bound_ctrl:1
	ds_read_b128 v[136:139], v48 offset:7936
	ds_read_b128 v[156:159], v49 offset:32
	v_add_f32_dpp v30, v15, v15 row_ror:1 row_mask:0xf bank_mask:0xf bound_ctrl:1
	s_waitcnt lgkmcnt(5)
	v_pk_fma_f32 v[10:11], v[96:97], v[30:31], v[16:17] op_sel_hi:[1,0,1] neg_lo:[0,1,0] neg_hi:[0,1,0]
	v_pk_fma_f32 v[8:9], v[98:99], v[30:31], v[18:19] op_sel_hi:[1,0,1] neg_lo:[0,1,0] neg_hi:[0,1,0]
	v_pk_mul_f32 v[24:25], v[10:11], v[100:101] op_sel:[0,0] op_sel_hi:[0,1]
	v_pk_fma_f32 v[24:25], v[10:11], v[102:103], v[24:25] op_sel:[1,0,0] op_sel_hi:[1,1,1]
	v_pk_fma_f32 v[24:25], v[8:9], v[104:105], v[24:25] op_sel:[0,0,0] op_sel_hi:[0,1,1]
	v_pk_fma_f32 v[24:25], v[8:9], v[106:107], v[24:25] op_sel:[1,0,0] op_sel_hi:[1,1,1]
	v_pk_fma_f32 v[16:17], v[108:109], v[162:163], v[10:11] op_sel_hi:[1,0,1]
	v_pk_fma_f32 v[18:19], v[110:111], v[162:163], v[8:9] op_sel_hi:[1,0,1]
	v_add_f32_dpp v15, v24, v24 row_ror:8 row_mask:0xf bank_mask:0xf bound_ctrl:1
	v_add_f32_dpp v33, v25, v25 row_ror:8 row_mask:0xf bank_mask:0xf bound_ctrl:1
	ds_read_b128 v[76:79], v48 offset:8192
	v_add_f32_dpp v15, v15, v15 row_ror:4 row_mask:0xf bank_mask:0xf bound_ctrl:1
	ds_read_b128 v[80:83], v48 offset:8448
	ds_read_b128 v[84:87], v48 offset:8704
	v_add_f32_dpp v15, v15, v15 row_ror:2 row_mask:0xf bank_mask:0xf bound_ctrl:1
	ds_read_b128 v[88:91], v48 offset:8960
	ds_read_b128 v[144:147], v48 offset:33024
	v_add_f32_dpp v30, v15, v15 row_ror:1 row_mask:0xf bank_mask:0xf bound_ctrl:1
	ds_write2st64_b32 v50, v32, v33 offset0:8 offset1:10
	s_waitcnt lgkmcnt(6)
	v_pk_fma_f32 v[10:11], v[112:113], v[30:31], v[16:17] op_sel_hi:[1,0,1] neg_lo:[0,1,0] neg_hi:[0,1,0]
	v_pk_fma_f32 v[8:9], v[114:115], v[30:31], v[18:19] op_sel_hi:[1,0,1] neg_lo:[0,1,0] neg_hi:[0,1,0]
	v_pk_mul_f32 v[24:25], v[10:11], v[116:117] op_sel:[0,0] op_sel_hi:[0,1]
	v_pk_fma_f32 v[24:25], v[10:11], v[118:119], v[24:25] op_sel:[1,0,0] op_sel_hi:[1,1,1]
	v_pk_fma_f32 v[24:25], v[8:9], v[120:121], v[24:25] op_sel:[0,0,0] op_sel_hi:[0,1,1]
	v_pk_fma_f32 v[24:25], v[8:9], v[122:123], v[24:25] op_sel:[1,0,0] op_sel_hi:[1,1,1]
	v_pk_fma_f32 v[16:17], v[124:125], v[162:163], v[10:11] op_sel:[0,1,0] op_sel_hi:[1,1,1]
	v_pk_fma_f32 v[18:19], v[126:127], v[162:163], v[8:9] op_sel:[0,1,0] op_sel_hi:[1,1,1]
	v_add_f32_dpp v15, v24, v24 row_ror:8 row_mask:0xf bank_mask:0xf bound_ctrl:1
	v_add_f32_dpp v32, v25, v25 row_ror:8 row_mask:0xf bank_mask:0xf bound_ctrl:1
	ds_read_b128 v[92:95], v48 offset:9216
	v_add_f32_dpp v15, v15, v15 row_ror:4 row_mask:0xf bank_mask:0xf bound_ctrl:1
	ds_read_b128 v[96:99], v48 offset:9472
	ds_read_b128 v[100:103], v48 offset:9728
	v_add_f32_dpp v15, v15, v15 row_ror:2 row_mask:0xf bank_mask:0xf bound_ctrl:1
	ds_read_b128 v[104:107], v48 offset:9984
	s_nop 0
	v_add_f32_dpp v30, v15, v15 row_ror:1 row_mask:0xf bank_mask:0xf bound_ctrl:1
	s_waitcnt lgkmcnt(4)
	v_pk_fma_f32 v[10:11], v[128:129], v[30:31], v[16:17] op_sel_hi:[1,0,1] neg_lo:[0,1,0] neg_hi:[0,1,0]
	v_pk_fma_f32 v[8:9], v[130:131], v[30:31], v[18:19] op_sel_hi:[1,0,1] neg_lo:[0,1,0] neg_hi:[0,1,0]
	v_pk_mul_f32 v[24:25], v[10:11], v[132:133] op_sel:[0,0] op_sel_hi:[0,1]
	v_pk_fma_f32 v[24:25], v[10:11], v[134:135], v[24:25] op_sel:[1,0,0] op_sel_hi:[1,1,1]
	v_pk_fma_f32 v[24:25], v[8:9], v[136:137], v[24:25] op_sel:[0,0,0] op_sel_hi:[0,1,1]
	v_pk_fma_f32 v[24:25], v[8:9], v[138:139], v[24:25] op_sel:[1,0,0] op_sel_hi:[1,1,1]
	s_nop 1
	v_add_f32_dpp v33, v25, v25 row_ror:8 row_mask:0xf bank_mask:0xf bound_ctrl:1
	ds_read_b128 v[108:111], v48 offset:10240
	ds_read_b128 v[112:115], v48 offset:10496
	ds_read_b128 v[116:119], v48 offset:10752
	ds_read_b128 v[120:123], v48 offset:11008
	ds_write2st64_b32 v50, v32, v33 offset0:12 offset1:14
	v_pk_mul_f32 v[10:11], v[10:11], v[140:141]
	v_pk_mul_f32 v[8:9], v[8:9], v[142:143]
	v_pk_mul_f32 v[24:25], v[10:11], v[144:145]
	v_pk_fma_f32 v[24:25], v[8:9], v[146:147], v[24:25]
	v_add_f32_e32 v24, v24, v25
	v_pk_fma_f32 v[16:17], v[76:77], v[156:157], v[10:11] op_sel_hi:[1,0,1]
	v_pk_fma_f32 v[18:19], v[78:79], v[156:157], v[8:9] op_sel_hi:[1,0,1]
	v_add_f32_dpp v15, v24, v24 row_ror:8 row_mask:0xf bank_mask:0xf bound_ctrl:1
	s_nop 1
	v_add_f32_dpp v15, v15, v15 row_ror:4 row_mask:0xf bank_mask:0xf bound_ctrl:1
	s_nop 1
	v_add_f32_dpp v15, v15, v15 row_ror:2 row_mask:0xf bank_mask:0xf bound_ctrl:1
	s_nop 1
	v_add_f32_dpp v30, v15, v15 row_ror:1 row_mask:0xf bank_mask:0xf bound_ctrl:1
	s_waitcnt lgkmcnt(5)
	v_pk_fma_f32 v[10:11], v[80:81], v[30:31], v[16:17] op_sel_hi:[1,0,1] neg_lo:[0,1,0] neg_hi:[0,1,0]
	v_pk_fma_f32 v[8:9], v[82:83], v[30:31], v[18:19] op_sel_hi:[1,0,1] neg_lo:[0,1,0] neg_hi:[0,1,0]
	v_pk_mul_f32 v[24:25], v[10:11], v[84:85] op_sel:[0,0] op_sel_hi:[0,1]
	v_pk_fma_f32 v[24:25], v[10:11], v[86:87], v[24:25] op_sel:[1,0,0] op_sel_hi:[1,1,1]
	v_pk_fma_f32 v[24:25], v[8:9], v[88:89], v[24:25] op_sel:[0,0,0] op_sel_hi:[0,1,1]
	v_pk_fma_f32 v[24:25], v[8:9], v[90:91], v[24:25] op_sel:[1,0,0] op_sel_hi:[1,1,1]
	v_pk_fma_f32 v[16:17], v[92:93], v[156:157], v[10:11] op_sel:[0,1,0] op_sel_hi:[1,1,1]
	v_pk_fma_f32 v[18:19], v[94:95], v[156:157], v[8:9] op_sel:[0,1,0] op_sel_hi:[1,1,1]
	v_add_f32_dpp v15, v24, v24 row_ror:8 row_mask:0xf bank_mask:0xf bound_ctrl:1
	v_add_f32_dpp v32, v25, v25 row_ror:8 row_mask:0xf bank_mask:0xf bound_ctrl:1
	ds_read_b128 v[124:127], v48 offset:11264
	v_add_f32_dpp v15, v15, v15 row_ror:4 row_mask:0xf bank_mask:0xf bound_ctrl:1
	ds_read_b128 v[128:131], v48 offset:11520
	ds_read_b128 v[132:135], v48 offset:11776
	v_add_f32_dpp v15, v15, v15 row_ror:2 row_mask:0xf bank_mask:0xf bound_ctrl:1
	ds_read_b128 v[136:139], v48 offset:12032
	ds_read_b128 v[160:163], v49 offset:48
	v_add_f32_dpp v30, v15, v15 row_ror:1 row_mask:0xf bank_mask:0xf bound_ctrl:1
	s_waitcnt lgkmcnt(5)
	v_pk_fma_f32 v[10:11], v[96:97], v[30:31], v[16:17] op_sel_hi:[1,0,1] neg_lo:[0,1,0] neg_hi:[0,1,0]
	v_pk_fma_f32 v[8:9], v[98:99], v[30:31], v[18:19] op_sel_hi:[1,0,1] neg_lo:[0,1,0] neg_hi:[0,1,0]
	v_pk_mul_f32 v[24:25], v[10:11], v[100:101] op_sel:[0,0] op_sel_hi:[0,1]
	v_pk_fma_f32 v[24:25], v[10:11], v[102:103], v[24:25] op_sel:[1,0,0] op_sel_hi:[1,1,1]
	v_pk_fma_f32 v[24:25], v[8:9], v[104:105], v[24:25] op_sel:[0,0,0] op_sel_hi:[0,1,1]
	v_pk_fma_f32 v[24:25], v[8:9], v[106:107], v[24:25] op_sel:[1,0,0] op_sel_hi:[1,1,1]
	v_pk_fma_f32 v[16:17], v[108:109], v[158:159], v[10:11] op_sel_hi:[1,0,1]
	v_pk_fma_f32 v[18:19], v[110:111], v[158:159], v[8:9] op_sel_hi:[1,0,1]
	v_add_f32_dpp v15, v24, v24 row_ror:8 row_mask:0xf bank_mask:0xf bound_ctrl:1
	v_add_f32_dpp v33, v25, v25 row_ror:8 row_mask:0xf bank_mask:0xf bound_ctrl:1
	ds_read_b128 v[76:79], v48 offset:12288
	v_add_f32_dpp v15, v15, v15 row_ror:4 row_mask:0xf bank_mask:0xf bound_ctrl:1
	ds_read_b128 v[80:83], v48 offset:12544
	ds_read_b128 v[84:87], v48 offset:12800
	v_add_f32_dpp v15, v15, v15 row_ror:2 row_mask:0xf bank_mask:0xf bound_ctrl:1
	ds_read_b128 v[88:91], v48 offset:13056
	s_nop 0
	v_add_f32_dpp v30, v15, v15 row_ror:1 row_mask:0xf bank_mask:0xf bound_ctrl:1
	ds_write2st64_b32 v50, v32, v33 offset0:16 offset1:18
	s_waitcnt lgkmcnt(5)
	v_pk_fma_f32 v[10:11], v[112:113], v[30:31], v[16:17] op_sel_hi:[1,0,1] neg_lo:[0,1,0] neg_hi:[0,1,0]
	v_pk_fma_f32 v[8:9], v[114:115], v[30:31], v[18:19] op_sel_hi:[1,0,1] neg_lo:[0,1,0] neg_hi:[0,1,0]
	v_pk_mul_f32 v[24:25], v[10:11], v[116:117] op_sel:[0,0] op_sel_hi:[0,1]
	v_pk_fma_f32 v[24:25], v[10:11], v[118:119], v[24:25] op_sel:[1,0,0] op_sel_hi:[1,1,1]
	v_pk_fma_f32 v[24:25], v[8:9], v[120:121], v[24:25] op_sel:[0,0,0] op_sel_hi:[0,1,1]
	v_pk_fma_f32 v[24:25], v[8:9], v[122:123], v[24:25] op_sel:[1,0,0] op_sel_hi:[1,1,1]
	v_pk_fma_f32 v[16:17], v[124:125], v[158:159], v[10:11] op_sel:[0,1,0] op_sel_hi:[1,1,1]
	v_pk_fma_f32 v[18:19], v[126:127], v[158:159], v[8:9] op_sel:[0,1,0] op_sel_hi:[1,1,1]
	v_add_f32_dpp v15, v24, v24 row_ror:8 row_mask:0xf bank_mask:0xf bound_ctrl:1
	v_add_f32_dpp v32, v25, v25 row_ror:8 row_mask:0xf bank_mask:0xf bound_ctrl:1
	ds_read_b128 v[92:95], v48 offset:13312
	v_add_f32_dpp v15, v15, v15 row_ror:4 row_mask:0xf bank_mask:0xf bound_ctrl:1
	ds_read_b128 v[96:99], v48 offset:13568
	ds_read_b128 v[100:103], v48 offset:13824
	v_add_f32_dpp v15, v15, v15 row_ror:2 row_mask:0xf bank_mask:0xf bound_ctrl:1
	ds_read_b128 v[104:107], v48 offset:14080
	s_nop 0
	v_add_f32_dpp v30, v15, v15 row_ror:1 row_mask:0xf bank_mask:0xf bound_ctrl:1
	s_waitcnt lgkmcnt(4)
	v_pk_fma_f32 v[10:11], v[128:129], v[30:31], v[16:17] op_sel_hi:[1,0,1] neg_lo:[0,1,0] neg_hi:[0,1,0]
	v_pk_fma_f32 v[8:9], v[130:131], v[30:31], v[18:19] op_sel_hi:[1,0,1] neg_lo:[0,1,0] neg_hi:[0,1,0]
	v_pk_mul_f32 v[24:25], v[10:11], v[132:133] op_sel:[0,0] op_sel_hi:[0,1]
	v_pk_fma_f32 v[24:25], v[10:11], v[134:135], v[24:25] op_sel:[1,0,0] op_sel_hi:[1,1,1]
	v_pk_fma_f32 v[24:25], v[8:9], v[136:137], v[24:25] op_sel:[0,0,0] op_sel_hi:[0,1,1]
	v_pk_fma_f32 v[24:25], v[8:9], v[138:139], v[24:25] op_sel:[1,0,0] op_sel_hi:[1,1,1]
	v_pk_fma_f32 v[16:17], v[76:77], v[160:161], v[10:11] op_sel_hi:[1,0,1]
	v_pk_fma_f32 v[18:19], v[78:79], v[160:161], v[8:9] op_sel_hi:[1,0,1]
	v_add_f32_dpp v15, v24, v24 row_ror:8 row_mask:0xf bank_mask:0xf bound_ctrl:1
	v_add_f32_dpp v33, v25, v25 row_ror:8 row_mask:0xf bank_mask:0xf bound_ctrl:1
	ds_read_b128 v[108:111], v48 offset:14336
	v_add_f32_dpp v15, v15, v15 row_ror:4 row_mask:0xf bank_mask:0xf bound_ctrl:1
	ds_read_b128 v[112:115], v48 offset:14592
	ds_read_b128 v[116:119], v48 offset:14848
	v_add_f32_dpp v15, v15, v15 row_ror:2 row_mask:0xf bank_mask:0xf bound_ctrl:1
	ds_read_b128 v[120:123], v48 offset:15104
	ds_read_b128 v[140:143], v48 offset:34048
	v_add_f32_dpp v30, v15, v15 row_ror:1 row_mask:0xf bank_mask:0xf bound_ctrl:1
	ds_write2st64_b32 v50, v32, v33 offset0:20 offset1:22
	s_waitcnt lgkmcnt(6)
	v_pk_fma_f32 v[10:11], v[80:81], v[30:31], v[16:17] op_sel_hi:[1,0,1] neg_lo:[0,1,0] neg_hi:[0,1,0]
	v_pk_fma_f32 v[8:9], v[82:83], v[30:31], v[18:19] op_sel_hi:[1,0,1] neg_lo:[0,1,0] neg_hi:[0,1,0]
	v_pk_mul_f32 v[24:25], v[10:11], v[84:85] op_sel:[0,0] op_sel_hi:[0,1]
	v_pk_fma_f32 v[24:25], v[10:11], v[86:87], v[24:25] op_sel:[1,0,0] op_sel_hi:[1,1,1]
	v_pk_fma_f32 v[24:25], v[8:9], v[88:89], v[24:25] op_sel:[0,0,0] op_sel_hi:[0,1,1]
	v_pk_fma_f32 v[24:25], v[8:9], v[90:91], v[24:25] op_sel:[1,0,0] op_sel_hi:[1,1,1]
	v_pk_fma_f32 v[16:17], v[92:93], v[160:161], v[10:11] op_sel:[0,1,0] op_sel_hi:[1,1,1]
	v_pk_fma_f32 v[18:19], v[94:95], v[160:161], v[8:9] op_sel:[0,1,0] op_sel_hi:[1,1,1]
	v_add_f32_dpp v15, v24, v24 row_ror:8 row_mask:0xf bank_mask:0xf bound_ctrl:1
	v_add_f32_dpp v32, v25, v25 row_ror:8 row_mask:0xf bank_mask:0xf bound_ctrl:1
	ds_read_b128 v[124:127], v48 offset:15360
	v_add_f32_dpp v15, v15, v15 row_ror:4 row_mask:0xf bank_mask:0xf bound_ctrl:1
	ds_read_b128 v[128:131], v48 offset:15616
	ds_read_b128 v[132:135], v48 offset:15872
	v_add_f32_dpp v15, v15, v15 row_ror:2 row_mask:0xf bank_mask:0xf bound_ctrl:1
	ds_read_b128 v[136:139], v48 offset:16128
	ds_read_b128 v[156:159], v49 offset:64
	v_add_f32_dpp v30, v15, v15 row_ror:1 row_mask:0xf bank_mask:0xf bound_ctrl:1
	s_waitcnt lgkmcnt(5)
	v_pk_fma_f32 v[10:11], v[96:97], v[30:31], v[16:17] op_sel_hi:[1,0,1] neg_lo:[0,1,0] neg_hi:[0,1,0]
	v_pk_fma_f32 v[8:9], v[98:99], v[30:31], v[18:19] op_sel_hi:[1,0,1] neg_lo:[0,1,0] neg_hi:[0,1,0]
	v_pk_mul_f32 v[24:25], v[10:11], v[100:101] op_sel:[0,0] op_sel_hi:[0,1]
	v_pk_fma_f32 v[24:25], v[10:11], v[102:103], v[24:25] op_sel:[1,0,0] op_sel_hi:[1,1,1]
	v_pk_fma_f32 v[24:25], v[8:9], v[104:105], v[24:25] op_sel:[0,0,0] op_sel_hi:[0,1,1]
	v_pk_fma_f32 v[24:25], v[8:9], v[106:107], v[24:25] op_sel:[1,0,0] op_sel_hi:[1,1,1]
	v_pk_fma_f32 v[16:17], v[108:109], v[162:163], v[10:11] op_sel_hi:[1,0,1]
	v_pk_fma_f32 v[18:19], v[110:111], v[162:163], v[8:9] op_sel_hi:[1,0,1]
	v_add_f32_dpp v15, v24, v24 row_ror:8 row_mask:0xf bank_mask:0xf bound_ctrl:1
	v_add_f32_dpp v33, v25, v25 row_ror:8 row_mask:0xf bank_mask:0xf bound_ctrl:1
	ds_read_b128 v[76:79], v48 offset:16384
	v_add_f32_dpp v15, v15, v15 row_ror:4 row_mask:0xf bank_mask:0xf bound_ctrl:1
	ds_read_b128 v[80:83], v48 offset:16640
	ds_read_b128 v[84:87], v48 offset:16896
	v_add_f32_dpp v15, v15, v15 row_ror:2 row_mask:0xf bank_mask:0xf bound_ctrl:1
	ds_read_b128 v[88:91], v48 offset:17152
	ds_read_b128 v[144:147], v48 offset:33280
	v_add_f32_dpp v30, v15, v15 row_ror:1 row_mask:0xf bank_mask:0xf bound_ctrl:1
	ds_write2st64_b32 v50, v32, v33 offset0:24 offset1:26
	s_waitcnt lgkmcnt(6)
	v_pk_fma_f32 v[10:11], v[112:113], v[30:31], v[16:17] op_sel_hi:[1,0,1] neg_lo:[0,1,0] neg_hi:[0,1,0]
	v_pk_fma_f32 v[8:9], v[114:115], v[30:31], v[18:19] op_sel_hi:[1,0,1] neg_lo:[0,1,0] neg_hi:[0,1,0]
	v_pk_mul_f32 v[24:25], v[10:11], v[116:117] op_sel:[0,0] op_sel_hi:[0,1]
	v_pk_fma_f32 v[24:25], v[10:11], v[118:119], v[24:25] op_sel:[1,0,0] op_sel_hi:[1,1,1]
	v_pk_fma_f32 v[24:25], v[8:9], v[120:121], v[24:25] op_sel:[0,0,0] op_sel_hi:[0,1,1]
	v_pk_fma_f32 v[24:25], v[8:9], v[122:123], v[24:25] op_sel:[1,0,0] op_sel_hi:[1,1,1]
	v_pk_fma_f32 v[16:17], v[124:125], v[162:163], v[10:11] op_sel:[0,1,0] op_sel_hi:[1,1,1]
	v_pk_fma_f32 v[18:19], v[126:127], v[162:163], v[8:9] op_sel:[0,1,0] op_sel_hi:[1,1,1]
	v_add_f32_dpp v15, v24, v24 row_ror:8 row_mask:0xf bank_mask:0xf bound_ctrl:1
	v_add_f32_dpp v32, v25, v25 row_ror:8 row_mask:0xf bank_mask:0xf bound_ctrl:1
	ds_read_b128 v[92:95], v48 offset:17408
	v_add_f32_dpp v15, v15, v15 row_ror:4 row_mask:0xf bank_mask:0xf bound_ctrl:1
	ds_read_b128 v[96:99], v48 offset:17664
	ds_read_b128 v[100:103], v48 offset:17920
	v_add_f32_dpp v15, v15, v15 row_ror:2 row_mask:0xf bank_mask:0xf bound_ctrl:1
	ds_read_b128 v[104:107], v48 offset:18176
	s_nop 0
	v_add_f32_dpp v30, v15, v15 row_ror:1 row_mask:0xf bank_mask:0xf bound_ctrl:1
	s_waitcnt lgkmcnt(4)
	v_pk_fma_f32 v[10:11], v[128:129], v[30:31], v[16:17] op_sel_hi:[1,0,1] neg_lo:[0,1,0] neg_hi:[0,1,0]
	v_pk_fma_f32 v[8:9], v[130:131], v[30:31], v[18:19] op_sel_hi:[1,0,1] neg_lo:[0,1,0] neg_hi:[0,1,0]
	v_pk_mul_f32 v[24:25], v[10:11], v[132:133] op_sel:[0,0] op_sel_hi:[0,1]
	v_pk_fma_f32 v[24:25], v[10:11], v[134:135], v[24:25] op_sel:[1,0,0] op_sel_hi:[1,1,1]
	v_pk_fma_f32 v[24:25], v[8:9], v[136:137], v[24:25] op_sel:[0,0,0] op_sel_hi:[0,1,1]
	v_pk_fma_f32 v[24:25], v[8:9], v[138:139], v[24:25] op_sel:[1,0,0] op_sel_hi:[1,1,1]
	s_nop 1
	v_add_f32_dpp v33, v25, v25 row_ror:8 row_mask:0xf bank_mask:0xf bound_ctrl:1
	ds_read_b128 v[108:111], v48 offset:18432
	ds_read_b128 v[112:115], v48 offset:18688
	ds_read_b128 v[116:119], v48 offset:18944
	ds_read_b128 v[120:123], v48 offset:19200
	ds_write2st64_b32 v50, v32, v33 offset0:28 offset1:30
	v_pk_mul_f32 v[10:11], v[10:11], v[140:141]
	v_pk_mul_f32 v[8:9], v[8:9], v[142:143]
	v_pk_mul_f32 v[24:25], v[10:11], v[144:145]
	v_pk_fma_f32 v[24:25], v[8:9], v[146:147], v[24:25]
	v_add_f32_e32 v24, v24, v25
	v_pk_fma_f32 v[16:17], v[76:77], v[156:157], v[10:11] op_sel_hi:[1,0,1]
	v_pk_fma_f32 v[18:19], v[78:79], v[156:157], v[8:9] op_sel_hi:[1,0,1]
	v_add_f32_dpp v15, v24, v24 row_ror:8 row_mask:0xf bank_mask:0xf bound_ctrl:1
	s_nop 1
	v_add_f32_dpp v15, v15, v15 row_ror:4 row_mask:0xf bank_mask:0xf bound_ctrl:1
	s_nop 1
	v_add_f32_dpp v15, v15, v15 row_ror:2 row_mask:0xf bank_mask:0xf bound_ctrl:1
	s_nop 1
	v_add_f32_dpp v30, v15, v15 row_ror:1 row_mask:0xf bank_mask:0xf bound_ctrl:1
	s_waitcnt lgkmcnt(5)
	v_pk_fma_f32 v[10:11], v[80:81], v[30:31], v[16:17] op_sel_hi:[1,0,1] neg_lo:[0,1,0] neg_hi:[0,1,0]
	v_pk_fma_f32 v[8:9], v[82:83], v[30:31], v[18:19] op_sel_hi:[1,0,1] neg_lo:[0,1,0] neg_hi:[0,1,0]
	v_pk_mul_f32 v[24:25], v[10:11], v[84:85] op_sel:[0,0] op_sel_hi:[0,1]
	v_pk_fma_f32 v[24:25], v[10:11], v[86:87], v[24:25] op_sel:[1,0,0] op_sel_hi:[1,1,1]
	v_pk_fma_f32 v[24:25], v[8:9], v[88:89], v[24:25] op_sel:[0,0,0] op_sel_hi:[0,1,1]
	v_pk_fma_f32 v[24:25], v[8:9], v[90:91], v[24:25] op_sel:[1,0,0] op_sel_hi:[1,1,1]
	v_pk_fma_f32 v[16:17], v[92:93], v[156:157], v[10:11] op_sel:[0,1,0] op_sel_hi:[1,1,1]
	v_pk_fma_f32 v[18:19], v[94:95], v[156:157], v[8:9] op_sel:[0,1,0] op_sel_hi:[1,1,1]
	v_add_f32_dpp v15, v24, v24 row_ror:8 row_mask:0xf bank_mask:0xf bound_ctrl:1
	v_add_f32_dpp v32, v25, v25 row_ror:8 row_mask:0xf bank_mask:0xf bound_ctrl:1
	ds_read_b128 v[124:127], v48 offset:19456
	v_add_f32_dpp v15, v15, v15 row_ror:4 row_mask:0xf bank_mask:0xf bound_ctrl:1
	ds_read_b128 v[128:131], v48 offset:19712
	ds_read_b128 v[132:135], v48 offset:19968
	v_add_f32_dpp v15, v15, v15 row_ror:2 row_mask:0xf bank_mask:0xf bound_ctrl:1
	ds_read_b128 v[136:139], v48 offset:20224
	ds_read_b128 v[160:163], v49 offset:80
	v_add_f32_dpp v30, v15, v15 row_ror:1 row_mask:0xf bank_mask:0xf bound_ctrl:1
	s_waitcnt lgkmcnt(5)
	v_pk_fma_f32 v[10:11], v[96:97], v[30:31], v[16:17] op_sel_hi:[1,0,1] neg_lo:[0,1,0] neg_hi:[0,1,0]
	v_pk_fma_f32 v[8:9], v[98:99], v[30:31], v[18:19] op_sel_hi:[1,0,1] neg_lo:[0,1,0] neg_hi:[0,1,0]
	v_pk_mul_f32 v[24:25], v[10:11], v[100:101] op_sel:[0,0] op_sel_hi:[0,1]
	v_pk_fma_f32 v[24:25], v[10:11], v[102:103], v[24:25] op_sel:[1,0,0] op_sel_hi:[1,1,1]
	v_pk_fma_f32 v[24:25], v[8:9], v[104:105], v[24:25] op_sel:[0,0,0] op_sel_hi:[0,1,1]
	v_pk_fma_f32 v[24:25], v[8:9], v[106:107], v[24:25] op_sel:[1,0,0] op_sel_hi:[1,1,1]
	v_pk_fma_f32 v[16:17], v[108:109], v[158:159], v[10:11] op_sel_hi:[1,0,1]
	v_pk_fma_f32 v[18:19], v[110:111], v[158:159], v[8:9] op_sel_hi:[1,0,1]
	v_add_f32_dpp v15, v24, v24 row_ror:8 row_mask:0xf bank_mask:0xf bound_ctrl:1
	v_add_f32_dpp v33, v25, v25 row_ror:8 row_mask:0xf bank_mask:0xf bound_ctrl:1
	ds_read_b128 v[76:79], v48 offset:20480
	v_add_f32_dpp v15, v15, v15 row_ror:4 row_mask:0xf bank_mask:0xf bound_ctrl:1
	ds_read_b128 v[80:83], v48 offset:20736
	ds_read_b128 v[84:87], v48 offset:20992
	v_add_f32_dpp v15, v15, v15 row_ror:2 row_mask:0xf bank_mask:0xf bound_ctrl:1
	ds_read_b128 v[88:91], v48 offset:21248
	s_nop 0
	v_add_f32_dpp v30, v15, v15 row_ror:1 row_mask:0xf bank_mask:0xf bound_ctrl:1
	ds_write2st64_b32 v50, v32, v33 offset0:32 offset1:34
	s_waitcnt lgkmcnt(5)
	v_pk_fma_f32 v[10:11], v[112:113], v[30:31], v[16:17] op_sel_hi:[1,0,1] neg_lo:[0,1,0] neg_hi:[0,1,0]
	v_pk_fma_f32 v[8:9], v[114:115], v[30:31], v[18:19] op_sel_hi:[1,0,1] neg_lo:[0,1,0] neg_hi:[0,1,0]
	v_pk_mul_f32 v[24:25], v[10:11], v[116:117] op_sel:[0,0] op_sel_hi:[0,1]
	v_pk_fma_f32 v[24:25], v[10:11], v[118:119], v[24:25] op_sel:[1,0,0] op_sel_hi:[1,1,1]
	v_pk_fma_f32 v[24:25], v[8:9], v[120:121], v[24:25] op_sel:[0,0,0] op_sel_hi:[0,1,1]
	v_pk_fma_f32 v[24:25], v[8:9], v[122:123], v[24:25] op_sel:[1,0,0] op_sel_hi:[1,1,1]
	v_pk_fma_f32 v[16:17], v[124:125], v[158:159], v[10:11] op_sel:[0,1,0] op_sel_hi:[1,1,1]
	v_pk_fma_f32 v[18:19], v[126:127], v[158:159], v[8:9] op_sel:[0,1,0] op_sel_hi:[1,1,1]
	v_add_f32_dpp v15, v24, v24 row_ror:8 row_mask:0xf bank_mask:0xf bound_ctrl:1
	v_add_f32_dpp v32, v25, v25 row_ror:8 row_mask:0xf bank_mask:0xf bound_ctrl:1
	ds_read_b128 v[92:95], v48 offset:21504
	v_add_f32_dpp v15, v15, v15 row_ror:4 row_mask:0xf bank_mask:0xf bound_ctrl:1
	ds_read_b128 v[96:99], v48 offset:21760
	ds_read_b128 v[100:103], v48 offset:22016
	v_add_f32_dpp v15, v15, v15 row_ror:2 row_mask:0xf bank_mask:0xf bound_ctrl:1
	ds_read_b128 v[104:107], v48 offset:22272
	s_nop 0
	v_add_f32_dpp v30, v15, v15 row_ror:1 row_mask:0xf bank_mask:0xf bound_ctrl:1
	s_waitcnt lgkmcnt(4)
	v_pk_fma_f32 v[10:11], v[128:129], v[30:31], v[16:17] op_sel_hi:[1,0,1] neg_lo:[0,1,0] neg_hi:[0,1,0]
	v_pk_fma_f32 v[8:9], v[130:131], v[30:31], v[18:19] op_sel_hi:[1,0,1] neg_lo:[0,1,0] neg_hi:[0,1,0]
	v_pk_mul_f32 v[24:25], v[10:11], v[132:133] op_sel:[0,0] op_sel_hi:[0,1]
	v_pk_fma_f32 v[24:25], v[10:11], v[134:135], v[24:25] op_sel:[1,0,0] op_sel_hi:[1,1,1]
	v_pk_fma_f32 v[24:25], v[8:9], v[136:137], v[24:25] op_sel:[0,0,0] op_sel_hi:[0,1,1]
	v_pk_fma_f32 v[24:25], v[8:9], v[138:139], v[24:25] op_sel:[1,0,0] op_sel_hi:[1,1,1]
	v_pk_fma_f32 v[16:17], v[76:77], v[160:161], v[10:11] op_sel_hi:[1,0,1]
	v_pk_fma_f32 v[18:19], v[78:79], v[160:161], v[8:9] op_sel_hi:[1,0,1]
	v_add_f32_dpp v15, v24, v24 row_ror:8 row_mask:0xf bank_mask:0xf bound_ctrl:1
	v_add_f32_dpp v33, v25, v25 row_ror:8 row_mask:0xf bank_mask:0xf bound_ctrl:1
	ds_read_b128 v[108:111], v48 offset:22528
	v_add_f32_dpp v15, v15, v15 row_ror:4 row_mask:0xf bank_mask:0xf bound_ctrl:1
	ds_read_b128 v[112:115], v48 offset:22784
	ds_read_b128 v[116:119], v48 offset:23040
	v_add_f32_dpp v15, v15, v15 row_ror:2 row_mask:0xf bank_mask:0xf bound_ctrl:1
	ds_read_b128 v[120:123], v48 offset:23296
	ds_read_b128 v[140:143], v48 offset:34304
	v_add_f32_dpp v30, v15, v15 row_ror:1 row_mask:0xf bank_mask:0xf bound_ctrl:1
	ds_write2st64_b32 v50, v32, v33 offset0:36 offset1:38
	s_waitcnt lgkmcnt(6)
	v_pk_fma_f32 v[10:11], v[80:81], v[30:31], v[16:17] op_sel_hi:[1,0,1] neg_lo:[0,1,0] neg_hi:[0,1,0]
	v_pk_fma_f32 v[8:9], v[82:83], v[30:31], v[18:19] op_sel_hi:[1,0,1] neg_lo:[0,1,0] neg_hi:[0,1,0]
	v_pk_mul_f32 v[24:25], v[10:11], v[84:85] op_sel:[0,0] op_sel_hi:[0,1]
	v_pk_fma_f32 v[24:25], v[10:11], v[86:87], v[24:25] op_sel:[1,0,0] op_sel_hi:[1,1,1]
	v_pk_fma_f32 v[24:25], v[8:9], v[88:89], v[24:25] op_sel:[0,0,0] op_sel_hi:[0,1,1]
	v_pk_fma_f32 v[24:25], v[8:9], v[90:91], v[24:25] op_sel:[1,0,0] op_sel_hi:[1,1,1]
	v_pk_fma_f32 v[16:17], v[92:93], v[160:161], v[10:11] op_sel:[0,1,0] op_sel_hi:[1,1,1]
	v_pk_fma_f32 v[18:19], v[94:95], v[160:161], v[8:9] op_sel:[0,1,0] op_sel_hi:[1,1,1]
	v_add_f32_dpp v15, v24, v24 row_ror:8 row_mask:0xf bank_mask:0xf bound_ctrl:1
	v_add_f32_dpp v32, v25, v25 row_ror:8 row_mask:0xf bank_mask:0xf bound_ctrl:1
	ds_read_b128 v[124:127], v48 offset:23552
	v_add_f32_dpp v15, v15, v15 row_ror:4 row_mask:0xf bank_mask:0xf bound_ctrl:1
	ds_read_b128 v[128:131], v48 offset:23808
	ds_read_b128 v[132:135], v48 offset:24064
	v_add_f32_dpp v15, v15, v15 row_ror:2 row_mask:0xf bank_mask:0xf bound_ctrl:1
	ds_read_b128 v[136:139], v48 offset:24320
	ds_read_b128 v[156:159], v49 offset:96
	v_add_f32_dpp v30, v15, v15 row_ror:1 row_mask:0xf bank_mask:0xf bound_ctrl:1
	s_waitcnt lgkmcnt(5)
	v_pk_fma_f32 v[10:11], v[96:97], v[30:31], v[16:17] op_sel_hi:[1,0,1] neg_lo:[0,1,0] neg_hi:[0,1,0]
	v_pk_fma_f32 v[8:9], v[98:99], v[30:31], v[18:19] op_sel_hi:[1,0,1] neg_lo:[0,1,0] neg_hi:[0,1,0]
	v_pk_mul_f32 v[24:25], v[10:11], v[100:101] op_sel:[0,0] op_sel_hi:[0,1]
	v_pk_fma_f32 v[24:25], v[10:11], v[102:103], v[24:25] op_sel:[1,0,0] op_sel_hi:[1,1,1]
	v_pk_fma_f32 v[24:25], v[8:9], v[104:105], v[24:25] op_sel:[0,0,0] op_sel_hi:[0,1,1]
	v_pk_fma_f32 v[24:25], v[8:9], v[106:107], v[24:25] op_sel:[1,0,0] op_sel_hi:[1,1,1]
	v_pk_fma_f32 v[16:17], v[108:109], v[162:163], v[10:11] op_sel_hi:[1,0,1]
	v_pk_fma_f32 v[18:19], v[110:111], v[162:163], v[8:9] op_sel_hi:[1,0,1]
	v_add_f32_dpp v15, v24, v24 row_ror:8 row_mask:0xf bank_mask:0xf bound_ctrl:1
	v_add_f32_dpp v33, v25, v25 row_ror:8 row_mask:0xf bank_mask:0xf bound_ctrl:1
	ds_read_b128 v[76:79], v48 offset:24576
	v_add_f32_dpp v15, v15, v15 row_ror:4 row_mask:0xf bank_mask:0xf bound_ctrl:1
	ds_read_b128 v[80:83], v48 offset:24832
	ds_read_b128 v[84:87], v48 offset:25088
	v_add_f32_dpp v15, v15, v15 row_ror:2 row_mask:0xf bank_mask:0xf bound_ctrl:1
	ds_read_b128 v[88:91], v48 offset:25344
	ds_read_b128 v[144:147], v48 offset:33536
	v_add_f32_dpp v30, v15, v15 row_ror:1 row_mask:0xf bank_mask:0xf bound_ctrl:1
	ds_write2st64_b32 v50, v32, v33 offset0:40 offset1:42
	s_waitcnt lgkmcnt(6)
	v_pk_fma_f32 v[10:11], v[112:113], v[30:31], v[16:17] op_sel_hi:[1,0,1] neg_lo:[0,1,0] neg_hi:[0,1,0]
	v_pk_fma_f32 v[8:9], v[114:115], v[30:31], v[18:19] op_sel_hi:[1,0,1] neg_lo:[0,1,0] neg_hi:[0,1,0]
	v_pk_mul_f32 v[24:25], v[10:11], v[116:117] op_sel:[0,0] op_sel_hi:[0,1]
	v_pk_fma_f32 v[24:25], v[10:11], v[118:119], v[24:25] op_sel:[1,0,0] op_sel_hi:[1,1,1]
	v_pk_fma_f32 v[24:25], v[8:9], v[120:121], v[24:25] op_sel:[0,0,0] op_sel_hi:[0,1,1]
	v_pk_fma_f32 v[24:25], v[8:9], v[122:123], v[24:25] op_sel:[1,0,0] op_sel_hi:[1,1,1]
	v_pk_fma_f32 v[16:17], v[124:125], v[162:163], v[10:11] op_sel:[0,1,0] op_sel_hi:[1,1,1]
	v_pk_fma_f32 v[18:19], v[126:127], v[162:163], v[8:9] op_sel:[0,1,0] op_sel_hi:[1,1,1]
	v_add_f32_dpp v15, v24, v24 row_ror:8 row_mask:0xf bank_mask:0xf bound_ctrl:1
	v_add_f32_dpp v32, v25, v25 row_ror:8 row_mask:0xf bank_mask:0xf bound_ctrl:1
	ds_read_b128 v[92:95], v48 offset:25600
	v_add_f32_dpp v15, v15, v15 row_ror:4 row_mask:0xf bank_mask:0xf bound_ctrl:1
	ds_read_b128 v[96:99], v48 offset:25856
	ds_read_b128 v[100:103], v48 offset:26112
	v_add_f32_dpp v15, v15, v15 row_ror:2 row_mask:0xf bank_mask:0xf bound_ctrl:1
	ds_read_b128 v[104:107], v48 offset:26368
	s_nop 0
	v_add_f32_dpp v30, v15, v15 row_ror:1 row_mask:0xf bank_mask:0xf bound_ctrl:1
	s_waitcnt lgkmcnt(4)
	v_pk_fma_f32 v[10:11], v[128:129], v[30:31], v[16:17] op_sel_hi:[1,0,1] neg_lo:[0,1,0] neg_hi:[0,1,0]
	v_pk_fma_f32 v[8:9], v[130:131], v[30:31], v[18:19] op_sel_hi:[1,0,1] neg_lo:[0,1,0] neg_hi:[0,1,0]
	v_pk_mul_f32 v[24:25], v[10:11], v[132:133] op_sel:[0,0] op_sel_hi:[0,1]
	v_pk_fma_f32 v[24:25], v[10:11], v[134:135], v[24:25] op_sel:[1,0,0] op_sel_hi:[1,1,1]
	v_pk_fma_f32 v[24:25], v[8:9], v[136:137], v[24:25] op_sel:[0,0,0] op_sel_hi:[0,1,1]
	v_pk_fma_f32 v[24:25], v[8:9], v[138:139], v[24:25] op_sel:[1,0,0] op_sel_hi:[1,1,1]
	s_nop 1
	v_add_f32_dpp v33, v25, v25 row_ror:8 row_mask:0xf bank_mask:0xf bound_ctrl:1
	ds_read_b128 v[108:111], v48 offset:26624
	ds_read_b128 v[112:115], v48 offset:26880
	ds_read_b128 v[116:119], v48 offset:27136
	ds_read_b128 v[120:123], v48 offset:27392
	ds_write2st64_b32 v50, v32, v33 offset0:44 offset1:46
	v_pk_mul_f32 v[10:11], v[10:11], v[140:141]
	v_pk_mul_f32 v[8:9], v[8:9], v[142:143]
	v_pk_mul_f32 v[24:25], v[10:11], v[144:145]
	v_pk_fma_f32 v[24:25], v[8:9], v[146:147], v[24:25]
	v_add_f32_e32 v24, v24, v25
	v_pk_fma_f32 v[16:17], v[76:77], v[156:157], v[10:11] op_sel_hi:[1,0,1]
	v_pk_fma_f32 v[18:19], v[78:79], v[156:157], v[8:9] op_sel_hi:[1,0,1]
	v_add_f32_dpp v15, v24, v24 row_ror:8 row_mask:0xf bank_mask:0xf bound_ctrl:1
	s_nop 1
	v_add_f32_dpp v15, v15, v15 row_ror:4 row_mask:0xf bank_mask:0xf bound_ctrl:1
	s_nop 1
	v_add_f32_dpp v15, v15, v15 row_ror:2 row_mask:0xf bank_mask:0xf bound_ctrl:1
	s_nop 1
	v_add_f32_dpp v30, v15, v15 row_ror:1 row_mask:0xf bank_mask:0xf bound_ctrl:1
	s_waitcnt lgkmcnt(5)
	v_pk_fma_f32 v[10:11], v[80:81], v[30:31], v[16:17] op_sel_hi:[1,0,1] neg_lo:[0,1,0] neg_hi:[0,1,0]
	v_pk_fma_f32 v[8:9], v[82:83], v[30:31], v[18:19] op_sel_hi:[1,0,1] neg_lo:[0,1,0] neg_hi:[0,1,0]
	v_pk_mul_f32 v[24:25], v[10:11], v[84:85] op_sel:[0,0] op_sel_hi:[0,1]
	v_pk_fma_f32 v[24:25], v[10:11], v[86:87], v[24:25] op_sel:[1,0,0] op_sel_hi:[1,1,1]
	v_pk_fma_f32 v[24:25], v[8:9], v[88:89], v[24:25] op_sel:[0,0,0] op_sel_hi:[0,1,1]
	v_pk_fma_f32 v[24:25], v[8:9], v[90:91], v[24:25] op_sel:[1,0,0] op_sel_hi:[1,1,1]
	v_pk_fma_f32 v[16:17], v[92:93], v[156:157], v[10:11] op_sel:[0,1,0] op_sel_hi:[1,1,1]
	v_pk_fma_f32 v[18:19], v[94:95], v[156:157], v[8:9] op_sel:[0,1,0] op_sel_hi:[1,1,1]
	v_add_f32_dpp v15, v24, v24 row_ror:8 row_mask:0xf bank_mask:0xf bound_ctrl:1
	v_add_f32_dpp v32, v25, v25 row_ror:8 row_mask:0xf bank_mask:0xf bound_ctrl:1
	ds_read_b128 v[124:127], v48 offset:27648
	v_add_f32_dpp v15, v15, v15 row_ror:4 row_mask:0xf bank_mask:0xf bound_ctrl:1
	ds_read_b128 v[128:131], v48 offset:27904
	ds_read_b128 v[132:135], v48 offset:28160
	v_add_f32_dpp v15, v15, v15 row_ror:2 row_mask:0xf bank_mask:0xf bound_ctrl:1
	ds_read_b128 v[136:139], v48 offset:28416
	ds_read_b128 v[160:163], v49 offset:112
	v_add_f32_dpp v30, v15, v15 row_ror:1 row_mask:0xf bank_mask:0xf bound_ctrl:1
	s_waitcnt lgkmcnt(5)
	v_pk_fma_f32 v[10:11], v[96:97], v[30:31], v[16:17] op_sel_hi:[1,0,1] neg_lo:[0,1,0] neg_hi:[0,1,0]
	v_pk_fma_f32 v[8:9], v[98:99], v[30:31], v[18:19] op_sel_hi:[1,0,1] neg_lo:[0,1,0] neg_hi:[0,1,0]
	v_pk_mul_f32 v[24:25], v[10:11], v[100:101] op_sel:[0,0] op_sel_hi:[0,1]
	v_pk_fma_f32 v[24:25], v[10:11], v[102:103], v[24:25] op_sel:[1,0,0] op_sel_hi:[1,1,1]
	v_pk_fma_f32 v[24:25], v[8:9], v[104:105], v[24:25] op_sel:[0,0,0] op_sel_hi:[0,1,1]
	v_pk_fma_f32 v[24:25], v[8:9], v[106:107], v[24:25] op_sel:[1,0,0] op_sel_hi:[1,1,1]
	v_pk_fma_f32 v[16:17], v[108:109], v[158:159], v[10:11] op_sel_hi:[1,0,1]
	v_pk_fma_f32 v[18:19], v[110:111], v[158:159], v[8:9] op_sel_hi:[1,0,1]
	v_add_f32_dpp v15, v24, v24 row_ror:8 row_mask:0xf bank_mask:0xf bound_ctrl:1
	v_add_f32_dpp v33, v25, v25 row_ror:8 row_mask:0xf bank_mask:0xf bound_ctrl:1
	ds_read_b128 v[76:79], v48 offset:28672
	v_add_f32_dpp v15, v15, v15 row_ror:4 row_mask:0xf bank_mask:0xf bound_ctrl:1
	ds_read_b128 v[80:83], v48 offset:28928
	ds_read_b128 v[84:87], v48 offset:29184
	v_add_f32_dpp v15, v15, v15 row_ror:2 row_mask:0xf bank_mask:0xf bound_ctrl:1
	ds_read_b128 v[88:91], v48 offset:29440
	s_nop 0
	v_add_f32_dpp v30, v15, v15 row_ror:1 row_mask:0xf bank_mask:0xf bound_ctrl:1
	ds_write2st64_b32 v50, v32, v33 offset0:48 offset1:50
	ds_read_b128 v[56:59], v52
	s_waitcnt lgkmcnt(5)
	v_pk_fma_f32 v[10:11], v[112:113], v[30:31], v[16:17] op_sel_hi:[1,0,1] neg_lo:[0,1,0] neg_hi:[0,1,0]
	v_pk_fma_f32 v[8:9], v[114:115], v[30:31], v[18:19] op_sel_hi:[1,0,1] neg_lo:[0,1,0] neg_hi:[0,1,0]
	v_pk_mul_f32 v[24:25], v[10:11], v[116:117] op_sel:[0,0] op_sel_hi:[0,1]
	v_pk_fma_f32 v[24:25], v[10:11], v[118:119], v[24:25] op_sel:[1,0,0] op_sel_hi:[1,1,1]
	v_pk_fma_f32 v[24:25], v[8:9], v[120:121], v[24:25] op_sel:[0,0,0] op_sel_hi:[0,1,1]
	v_pk_fma_f32 v[24:25], v[8:9], v[122:123], v[24:25] op_sel:[1,0,0] op_sel_hi:[1,1,1]
	v_pk_fma_f32 v[16:17], v[124:125], v[158:159], v[10:11] op_sel:[0,1,0] op_sel_hi:[1,1,1]
	v_pk_fma_f32 v[18:19], v[126:127], v[158:159], v[8:9] op_sel:[0,1,0] op_sel_hi:[1,1,1]
	v_add_f32_dpp v15, v24, v24 row_ror:8 row_mask:0xf bank_mask:0xf bound_ctrl:1
	v_add_f32_dpp v32, v25, v25 row_ror:8 row_mask:0xf bank_mask:0xf bound_ctrl:1
	ds_read_b128 v[92:95], v48 offset:29696
	v_add_f32_dpp v15, v15, v15 row_ror:4 row_mask:0xf bank_mask:0xf bound_ctrl:1
	ds_read_b128 v[96:99], v48 offset:29952
	ds_read_b128 v[100:103], v48 offset:30208
	v_add_f32_dpp v15, v15, v15 row_ror:2 row_mask:0xf bank_mask:0xf bound_ctrl:1
	ds_read_b128 v[104:107], v48 offset:30464
	s_nop 0
	v_add_f32_dpp v30, v15, v15 row_ror:1 row_mask:0xf bank_mask:0xf bound_ctrl:1
	s_waitcnt lgkmcnt(4)
	v_min_u32_e32 v56, v56, v57
	v_min3_u32 v56, v56, v58, v59
	v_pk_fma_f32 v[10:11], v[128:129], v[30:31], v[16:17] op_sel_hi:[1,0,1] neg_lo:[0,1,0] neg_hi:[0,1,0]
	v_pk_fma_f32 v[8:9], v[130:131], v[30:31], v[18:19] op_sel_hi:[1,0,1] neg_lo:[0,1,0] neg_hi:[0,1,0]
	v_pk_mul_f32 v[24:25], v[10:11], v[132:133] op_sel:[0,0] op_sel_hi:[0,1]
	v_pk_fma_f32 v[24:25], v[10:11], v[134:135], v[24:25] op_sel:[1,0,0] op_sel_hi:[1,1,1]
	v_pk_fma_f32 v[24:25], v[8:9], v[136:137], v[24:25] op_sel:[0,0,0] op_sel_hi:[0,1,1]
	v_pk_fma_f32 v[24:25], v[8:9], v[138:139], v[24:25] op_sel:[1,0,0] op_sel_hi:[1,1,1]
	v_pk_fma_f32 v[16:17], v[76:77], v[160:161], v[10:11] op_sel_hi:[1,0,1]
	v_pk_fma_f32 v[18:19], v[78:79], v[160:161], v[8:9] op_sel_hi:[1,0,1]
	v_add_f32_dpp v15, v24, v24 row_ror:8 row_mask:0xf bank_mask:0xf bound_ctrl:1
	v_add_f32_dpp v33, v25, v25 row_ror:8 row_mask:0xf bank_mask:0xf bound_ctrl:1
	ds_read_b128 v[108:111], v48 offset:30720
	v_add_f32_dpp v15, v15, v15 row_ror:4 row_mask:0xf bank_mask:0xf bound_ctrl:1
	ds_read_b128 v[112:115], v48 offset:30976
	ds_read_b128 v[116:119], v48 offset:31232
	v_add_f32_dpp v15, v15, v15 row_ror:2 row_mask:0xf bank_mask:0xf bound_ctrl:1
	ds_read_b128 v[120:123], v48 offset:31488
	ds_read_b128 v[140:143], v48 offset:34560
	v_add_f32_dpp v30, v15, v15 row_ror:1 row_mask:0xf bank_mask:0xf bound_ctrl:1
	ds_write2st64_b32 v50, v32, v33 offset0:52 offset1:54
	s_waitcnt lgkmcnt(6)
	v_pk_fma_f32 v[10:11], v[80:81], v[30:31], v[16:17] op_sel_hi:[1,0,1] neg_lo:[0,1,0] neg_hi:[0,1,0]
	v_pk_fma_f32 v[8:9], v[82:83], v[30:31], v[18:19] op_sel_hi:[1,0,1] neg_lo:[0,1,0] neg_hi:[0,1,0]
	v_pk_mul_f32 v[24:25], v[10:11], v[84:85] op_sel:[0,0] op_sel_hi:[0,1]
	v_pk_fma_f32 v[24:25], v[10:11], v[86:87], v[24:25] op_sel:[1,0,0] op_sel_hi:[1,1,1]
	v_pk_fma_f32 v[24:25], v[8:9], v[88:89], v[24:25] op_sel:[0,0,0] op_sel_hi:[0,1,1]
	v_pk_fma_f32 v[24:25], v[8:9], v[90:91], v[24:25] op_sel:[1,0,0] op_sel_hi:[1,1,1]
	v_pk_fma_f32 v[16:17], v[92:93], v[160:161], v[10:11] op_sel:[0,1,0] op_sel_hi:[1,1,1]
	v_pk_fma_f32 v[18:19], v[94:95], v[160:161], v[8:9] op_sel:[0,1,0] op_sel_hi:[1,1,1]
	v_add_f32_dpp v15, v24, v24 row_ror:8 row_mask:0xf bank_mask:0xf bound_ctrl:1
	v_add_f32_dpp v32, v25, v25 row_ror:8 row_mask:0xf bank_mask:0xf bound_ctrl:1
	ds_read_b128 v[124:127], v48 offset:31744
	v_add_f32_dpp v15, v15, v15 row_ror:4 row_mask:0xf bank_mask:0xf bound_ctrl:1
	ds_read_b128 v[128:131], v48 offset:32000
	ds_read_b128 v[132:135], v48 offset:32256
	v_add_f32_dpp v15, v15, v15 row_ror:2 row_mask:0xf bank_mask:0xf bound_ctrl:1
	ds_read_b128 v[136:139], v48 offset:32512
	s_nop 0
	v_add_f32_dpp v30, v15, v15 row_ror:1 row_mask:0xf bank_mask:0xf bound_ctrl:1
	v_readfirstlane_b32 s54, v56
	s_add_u32 s64, s6, 2
	s_cmp_lt_u32 s54, s64
	s_cbranch_scc1 .Lss_spin_1
.Lss_ok_1:
	s_waitcnt lgkmcnt(4)
	v_pk_fma_f32 v[10:11], v[96:97], v[30:31], v[16:17] op_sel_hi:[1,0,1] neg_lo:[0,1,0] neg_hi:[0,1,0]
	v_pk_fma_f32 v[8:9], v[98:99], v[30:31], v[18:19] op_sel_hi:[1,0,1] neg_lo:[0,1,0] neg_hi:[0,1,0]
	v_pk_mul_f32 v[24:25], v[10:11], v[100:101] op_sel:[0,0] op_sel_hi:[0,1]
	v_pk_fma_f32 v[24:25], v[10:11], v[102:103], v[24:25] op_sel:[1,0,0] op_sel_hi:[1,1,1]
	v_pk_fma_f32 v[24:25], v[8:9], v[104:105], v[24:25] op_sel:[0,0,0] op_sel_hi:[0,1,1]
	v_pk_fma_f32 v[24:25], v[8:9], v[106:107], v[24:25] op_sel:[1,0,0] op_sel_hi:[1,1,1]
	v_pk_fma_f32 v[16:17], v[108:109], v[162:163], v[10:11] op_sel_hi:[1,0,1]
	v_pk_fma_f32 v[18:19], v[110:111], v[162:163], v[8:9] op_sel_hi:[1,0,1]
	v_add_f32_dpp v15, v24, v24 row_ror:8 row_mask:0xf bank_mask:0xf bound_ctrl:1
	v_add_f32_dpp v33, v25, v25 row_ror:8 row_mask:0xf bank_mask:0xf bound_ctrl:1
	ds_read_b128 v[76:79], v34 offset:0
	v_add_f32_dpp v15, v15, v15 row_ror:4 row_mask:0xf bank_mask:0xf bound_ctrl:1
	ds_read_b128 v[80:83], v34 offset:256
	ds_read_b128 v[84:87], v34 offset:512
	v_add_f32_dpp v15, v15, v15 row_ror:2 row_mask:0xf bank_mask:0xf bound_ctrl:1
	ds_read_b128 v[88:91], v34 offset:768
	ds_read_b128 v[144:147], v34 offset:32768
	v_add_f32_dpp v30, v15, v15 row_ror:1 row_mask:0xf bank_mask:0xf bound_ctrl:1
	ds_write2st64_b32 v50, v32, v33 offset0:56 offset1:58
	ds_read_b128 v[156:159], v35 offset:0
	s_waitcnt lgkmcnt(7)
	v_pk_fma_f32 v[10:11], v[112:113], v[30:31], v[16:17] op_sel_hi:[1,0,1] neg_lo:[0,1,0] neg_hi:[0,1,0]
	v_pk_fma_f32 v[8:9], v[114:115], v[30:31], v[18:19] op_sel_hi:[1,0,1] neg_lo:[0,1,0] neg_hi:[0,1,0]
	v_pk_mul_f32 v[24:25], v[10:11], v[116:117] op_sel:[0,0] op_sel_hi:[0,1]
	v_pk_fma_f32 v[24:25], v[10:11], v[118:119], v[24:25] op_sel:[1,0,0] op_sel_hi:[1,1,1]
	v_pk_fma_f32 v[24:25], v[8:9], v[120:121], v[24:25] op_sel:[0,0,0] op_sel_hi:[0,1,1]
	v_pk_fma_f32 v[24:25], v[8:9], v[122:123], v[24:25] op_sel:[1,0,0] op_sel_hi:[1,1,1]
	v_pk_fma_f32 v[16:17], v[124:125], v[162:163], v[10:11] op_sel:[0,1,0] op_sel_hi:[1,1,1]
	v_pk_fma_f32 v[18:19], v[126:127], v[162:163], v[8:9] op_sel:[0,1,0] op_sel_hi:[1,1,1]
	v_add_f32_dpp v15, v24, v24 row_ror:8 row_mask:0xf bank_mask:0xf bound_ctrl:1
	v_add_f32_dpp v32, v25, v25 row_ror:8 row_mask:0xf bank_mask:0xf bound_ctrl:1
	ds_read_b128 v[92:95], v34 offset:1024
	v_add_f32_dpp v15, v15, v15 row_ror:4 row_mask:0xf bank_mask:0xf bound_ctrl:1
	ds_read_b128 v[96:99], v34 offset:1280
	ds_read_b128 v[100:103], v34 offset:1536
	v_add_f32_dpp v15, v15, v15 row_ror:2 row_mask:0xf bank_mask:0xf bound_ctrl:1
	ds_read_b128 v[104:107], v34 offset:1792
	s_nop 0
	v_add_f32_dpp v30, v15, v15 row_ror:1 row_mask:0xf bank_mask:0xf bound_ctrl:1
	s_waitcnt lgkmcnt(4)
	v_pk_fma_f32 v[10:11], v[128:129], v[30:31], v[16:17] op_sel_hi:[1,0,1] neg_lo:[0,1,0] neg_hi:[0,1,0]
	v_pk_fma_f32 v[8:9], v[130:131], v[30:31], v[18:19] op_sel_hi:[1,0,1] neg_lo:[0,1,0] neg_hi:[0,1,0]
	v_pk_mul_f32 v[24:25], v[10:11], v[132:133] op_sel:[0,0] op_sel_hi:[0,1]
	v_pk_fma_f32 v[24:25], v[10:11], v[134:135], v[24:25] op_sel:[1,0,0] op_sel_hi:[1,1,1]
	v_pk_fma_f32 v[24:25], v[8:9], v[136:137], v[24:25] op_sel:[0,0,0] op_sel_hi:[0,1,1]
	v_pk_fma_f32 v[24:25], v[8:9], v[138:139], v[24:25] op_sel:[1,0,0] op_sel_hi:[1,1,1]
	s_nop 1
	v_add_f32_dpp v33, v25, v25 row_ror:8 row_mask:0xf bank_mask:0xf bound_ctrl:1
	ds_read_b128 v[108:111], v34 offset:2048
	ds_read_b128 v[112:115], v34 offset:2304
	ds_read_b128 v[116:119], v34 offset:2560
	ds_read_b128 v[120:123], v34 offset:2816
	ds_write2st64_b32 v50, v32, v33 offset0:60 offset1:62
	v_pk_mul_f32 v[10:11], v[10:11], v[140:141]
	v_pk_mul_f32 v[8:9], v[8:9], v[142:143]
	v_pk_mul_f32 v[24:25], v[10:11], v[144:145]
	v_pk_fma_f32 v[24:25], v[8:9], v[146:147], v[24:25]
	v_add_f32_e32 v24, v24, v25
	v_pk_fma_f32 v[16:17], v[76:77], v[156:157], v[10:11] op_sel_hi:[1,0,1]
	v_pk_fma_f32 v[18:19], v[78:79], v[156:157], v[8:9] op_sel_hi:[1,0,1]
	v_add_f32_dpp v15, v24, v24 row_ror:8 row_mask:0xf bank_mask:0xf bound_ctrl:1
	v_add_u32_e32 v51, 1, v51
	s_add_u32 s6, s6, 1
	v_add_f32_dpp v15, v15, v15 row_ror:4 row_mask:0xf bank_mask:0xf bound_ctrl:1
	ds_write_b32 v53, v51
	s_nop 0
	v_add_f32_dpp v15, v15, v15 row_ror:2 row_mask:0xf bank_mask:0xf bound_ctrl:1
	s_nop 1
	v_add_f32_dpp v30, v15, v15 row_ror:1 row_mask:0xf bank_mask:0xf bound_ctrl:1
	s_cmp_lt_u32 s6, 0x100
	s_cbranch_scc1 .Lsc_S_loop
	s_waitcnt lgkmcnt(0)
	s_branch .Lsc_item_end

.Lsc_G:
	v_add_u32_e32 v1, 0xffffff00, v173
	v_lshrrev_b32_e32 v2, 3, v1
	v_and_b32_e32 v3, 7, v1
	s_and_b32 s8, s4, 7
	s_bfe_u32 s10, s4, 0x20003
	s_lshr_b32 s11, s4, 7
	s_bfe_u32 s9, s4, 0x20005
	s_lshl_b32 s9, s9, 13
	v_readlane_b32 s50, v242, 0
	v_readlane_b32 s51, v242, 1
	v_readlane_b32 s16, v242, 62
	s_load_dwordx4 s[12:15], s[50:51], 0x68
	s_add_u32 s36, s90, 0x5e00000
	s_addc_u32 s37, s91, 0
	s_add_u32 s38, s90, 0x7e00000
	s_addc_u32 s39, s91, 0
	s_add_u32 s44, s90, 0x9e00000
	s_addc_u32 s45, s91, 0
	s_add_u32 s46, s90, 0x1c00000
	s_addc_u32 s47, s91, 0
	s_lshl_b32 s68, s11, 25
	s_add_u32 s69, s68, 0x13e00000
	s_add_u32 s40, s90, s69
	s_addc_u32 s41, s91, 0
	s_add_u32 s69, s68, 0x17e00000
	s_add_u32 s42, s90, s69
	s_addc_u32 s43, s91, 0
	s_lshl_b32 s68, s11, 26
	s_add_u32 s68, s68, 0xbe00000
	s_add_u32 s48, s90, s68
	s_addc_u32 s49, s91, 0
	s_cmp_eq_u32 s11, 0
	s_mov_b32 s54, 0x8000
	s_movk_i32 s55, 0x400
	s_mov_b32 s64, 0x10000
	s_cselect_b32 s54, s54, 0xffff8000
	s_cselect_b32 s55, s55, 0xfffffc00
	s_cselect_b32 s64, s64, 0xffff0000
	s_cselect_b64 vcc, -1, 0
	v_sub_u32_e32 v4, 0x1fff, v2
	s_nop 3
	v_cndmask_b32_e32 v4, v4, v2, vcc
	v_add_u32_e32 v4, s9, v4
	s_lshl_b32 s68, s8, 7
	v_lshlrev_b32_e32 v5, 10, v4
	v_lshl_add_u32 v5, v3, 3, v5
	v_add_u32_e32 v5, s68, v5
	s_lshl_b32 s69, s8, 2
	v_lshlrev_b32_e32 v6, 5, v4
	v_add_u32_e32 v6, s69, v6
	s_lshl_b32 s69, s10, 5
	s_add_i32 s69, s69, s68
	v_lshlrev_b32_e32 v9, 10, v4
	v_lshl_add_u32 v9, v3, 2, v9
	v_add_u32_e32 v9, s69, v9
	s_lshl_b32 s69, s69, 1
	v_lshlrev_b32_e32 v7, 11, v4
	v_lshl_add_u32 v7, v3, 3, v7
	v_add_u32_e32 v7, s69, v7
	v_mul_u32_u24_e32 v8, 1024, v2
	v_lshl_add_u32 v8, v3, 4, v8
	v_add_u32_e32 v138, 512, v8
	v_add_u32_e32 v140, 35328, v8
	v_add_u32_e32 v152, -4, v0
	v_lshlrev_b32_e32 v152, 12, v152
	v_add_u32_e32 v152, 107072, v152
	v_and_b32_e32 v156, 7, v2
	v_lshlrev_b32_e32 v153, 8, v156
	v_lshl_add_u32 v153, v3, 4, v153
	v_add_u32_e32 v153, v152, v153
	v_and_b32_e32 v154, 63, v1
	v_lshl_add_u32 v154, v154, 2, v152
	v_add_u32_e32 v155, 2048, v154
	v_add_u32_e32 v139, -1, v2
	v_mul_u32_u24_e32 v139, 1024, v139
	v_lshl_add_u32 v139, v3, 4, v139
	v_add_u32_e32 v141, 35328, v139
	v_add_u32_e32 v139, 512, v139
	v_cmp_eq_u32_e32 vcc, 0, v2
	s_nop 1
	v_cndmask_b32_e32 v139, v139, v152, vcc
	v_cndmask_b32_e32 v141, v141, v152, vcc
	v_lshrrev_b32_e32 v158, 3, v2
	v_lshlrev_b32_e32 v158, 8, v158
	v_lshl_add_u32 v158, v3, 4, v158
	v_add_u32_e32 v159, 33792, v158
	v_add_u32_e32 v158, 32768, v158
	v_mul_u32_u24_e32 v142, 288, v3
	v_lshl_add_u32 v142, v2, 2, v142
	v_add_u32_e32 v143, 71936, v142
	v_add_u32_e32 v142, 69632, v142
	v_lshlrev_b32_e32 v11, 9, v2
	v_lshl_add_u32 v11, v3, 6, v11
	v_add_u32_e32 v11, 74240, v11
	s_lshl_b32 s69, s8, 6
	s_add_i32 s69, s69, s16
	v_lshl_add_u32 v106, v3, 2, s69
	v_lshlrev_b32_e32 v106, 2, v106
	s_waitcnt lgkmcnt(0)
	global_load_dwordx4 v[12:15], v106, s[12:13]
	global_load_dwordx4 v[16:19], v106, s[12:13] offset:128
	global_load_dwordx4 v[20:23], v106, s[14:15]
	global_load_dwordx4 v[24:27], v106, s[14:15] offset:128
	global_load_dwordx2 v[28:29], v5, s[36:37]
	global_load_dwordx2 v[30:31], v5, s[36:37] offset:64
	global_load_dwordx2 v[32:33], v5, s[38:39]
	global_load_dwordx2 v[34:35], v5, s[38:39] offset:64
	global_load_dwordx2 v[36:37], v5, s[40:41]
	global_load_dwordx2 v[38:39], v5, s[40:41] offset:64
	global_load_dwordx2 v[40:41], v5, s[42:43]
	global_load_dwordx2 v[42:43], v5, s[42:43] offset:64
	global_load_dword v44, v6, s[46:47]
	global_load_dword v45, v9, s[44:45]
	v_add_u32_e32 v5, s54, v5
	v_add_u32_e32 v6, s55, v6
	v_add_u32_e32 v9, s54, v9
	global_load_dwordx2 v[46:47], v5, s[36:37]
	global_load_dwordx2 v[48:49], v5, s[36:37] offset:64
	global_load_dwordx2 v[50:51], v5, s[38:39]
	global_load_dwordx2 v[52:53], v5, s[38:39] offset:64
	global_load_dwordx2 v[54:55], v5, s[40:41]
	global_load_dwordx2 v[56:57], v5, s[40:41] offset:64
	global_load_dwordx2 v[58:59], v5, s[42:43]
	global_load_dwordx2 v[60:61], v5, s[42:43] offset:64
	global_load_dword v62, v6, s[46:47]
	global_load_dword v63, v9, s[44:45]
	v_add_u32_e32 v5, s54, v5
	v_add_u32_e32 v6, s55, v6
	v_add_u32_e32 v9, s54, v9
	v_cmp_eq_u32_e64 s[12:13], 0, v156
	v_cmp_eq_u32_e64 s[14:15], 7, v156
	s_mov_b32 s6, 0
	v_mov_b32_e32 v144, 107024
	v_mov_b32_e32 v145, v164
	v_mov_b32_e32 v146, 0

.Lsc_G_wd_0:
	v_lshlrev_b32_e32 v64, 16, v36
	v_and_b32_e32 v65, 0xffff0000, v36
	v_mul_f32_e32 v64, 0x3fb8aa3b, v64
	v_mul_f32_e32 v65, 0x3fb8aa3b, v65
	v_lshlrev_b32_e32 v66, 16, v37
	v_and_b32_e32 v67, 0xffff0000, v37
	v_mul_f32_e32 v66, 0x3fb8aa3b, v66
	v_mul_f32_e32 v67, 0x3fb8aa3b, v67
	v_lshlrev_b32_e32 v68, 16, v38
	v_and_b32_e32 v69, 0xffff0000, v38
	v_mul_f32_e32 v68, 0x3fb8aa3b, v68
	v_mul_f32_e32 v69, 0x3fb8aa3b, v69
	v_lshlrev_b32_e32 v70, 16, v39
	v_and_b32_e32 v71, 0xffff0000, v39
	v_mul_f32_e32 v70, 0x3fb8aa3b, v70
	v_mul_f32_e32 v71, 0x3fb8aa3b, v71
	ds_write_b128 v153, v[64:67]
	ds_write_b128 v153, v[68:71] offset:128
	s_waitcnt lgkmcnt(0)
	ds_read_b32 v124, v154 offset:0
	ds_read_b32 v125, v154 offset:256
	ds_read_b32 v126, v154 offset:512
	ds_read_b32 v127, v154 offset:768
	ds_read_b32 v128, v154 offset:1024
	ds_read_b32 v129, v154 offset:1280
	ds_read_b32 v130, v154 offset:1536
	ds_read_b32 v131, v154 offset:1792
	v_lshlrev_b32_e32 v108, 16, v32
	v_and_b32_e32 v109, 0xffff0000, v32
	v_lshlrev_b32_e32 v110, 16, v40
	v_and_b32_e32 v111, 0xffff0000, v40
	v_lshlrev_b32_e32 v96, 16, v28
	v_and_b32_e32 v97, 0xffff0000, v28
	v_pk_add_f32 v[112:113], v[110:111], -1.0 op_sel_hi:[1,0]
	v_pk_mul_f32 v[114:115], v[12:13], v[108:109]
	v_pk_fma_f32 v[112:113], v[20:21], v[112:113], 1.0 op_sel_hi:[1,1,0]
	v_pk_mul_f32 v[88:89], v[44:45], v[114:115] op_sel_hi:[0,1]
	v_pk_mul_f32 v[72:73], v[112:113], v[108:109]
	v_pk_mul_f32 v[80:81], v[88:89], v[110:111]
	v_lshlrev_b32_e32 v108, 16, v33
	v_and_b32_e32 v109, 0xffff0000, v33
	v_lshlrev_b32_e32 v110, 16, v41
	v_and_b32_e32 v111, 0xffff0000, v41
	v_lshlrev_b32_e32 v98, 16, v29
	v_and_b32_e32 v99, 0xffff0000, v29
	v_pk_add_f32 v[112:113], v[110:111], -1.0 op_sel_hi:[1,0]
	v_pk_mul_f32 v[114:115], v[14:15], v[108:109]
	v_pk_fma_f32 v[112:113], v[22:23], v[112:113], 1.0 op_sel_hi:[1,1,0]
	v_pk_mul_f32 v[90:91], v[44:45], v[114:115] op_sel_hi:[0,1]
	v_pk_mul_f32 v[74:75], v[112:113], v[108:109]
	v_pk_mul_f32 v[82:83], v[90:91], v[110:111]
	v_lshlrev_b32_e32 v108, 16, v34
	v_and_b32_e32 v109, 0xffff0000, v34
	v_lshlrev_b32_e32 v110, 16, v42
	v_and_b32_e32 v111, 0xffff0000, v42
	v_lshlrev_b32_e32 v100, 16, v30
	v_and_b32_e32 v101, 0xffff0000, v30
	v_pk_add_f32 v[112:113], v[110:111], -1.0 op_sel_hi:[1,0]
	v_pk_mul_f32 v[114:115], v[16:17], v[108:109]
	v_pk_fma_f32 v[112:113], v[24:25], v[112:113], 1.0 op_sel_hi:[1,1,0]
	v_pk_mul_f32 v[92:93], v[44:45], v[114:115] op_sel_hi:[0,1]
	v_pk_mul_f32 v[76:77], v[112:113], v[108:109]
	v_pk_mul_f32 v[84:85], v[92:93], v[110:111]
	v_lshlrev_b32_e32 v108, 16, v35
	v_and_b32_e32 v109, 0xffff0000, v35
	v_lshlrev_b32_e32 v110, 16, v43
	v_and_b32_e32 v111, 0xffff0000, v43
	v_lshlrev_b32_e32 v102, 16, v31
	v_and_b32_e32 v103, 0xffff0000, v31
	v_pk_add_f32 v[112:113], v[110:111], -1.0 op_sel_hi:[1,0]
	v_pk_mul_f32 v[114:115], v[18:19], v[108:109]
	v_pk_fma_f32 v[112:113], v[26:27], v[112:113], 1.0 op_sel_hi:[1,1,0]
	v_pk_mul_f32 v[94:95], v[44:45], v[114:115] op_sel_hi:[0,1]
	v_pk_mul_f32 v[78:79], v[112:113], v[108:109]
	v_pk_mul_f32 v[86:87], v[94:95], v[110:111]
	v_lshlrev_b32_e32 v104, 16, v45
	v_and_b32_e32 v105, 0xffff0000, v45
	s_waitcnt lgkmcnt(0)
	v_add_f32_e32 v125, v124, v125
	v_add_f32_e32 v126, v125, v126
	v_add_f32_e32 v127, v126, v127
	v_add_f32_e32 v128, v127, v128
	v_add_f32_e32 v129, v128, v129
	v_add_f32_e32 v130, v129, v130
	v_add_f32_e32 v131, v130, v131
	ds_write_b32 v155, v124 offset:0
	ds_write_b32 v155, v125 offset:256
	ds_write_b32 v155, v126 offset:512
	ds_write_b32 v155, v127 offset:768
	ds_write_b32 v155, v128 offset:1024
	ds_write_b32 v155, v129 offset:1280
	ds_write_b32 v155, v130 offset:1536
	ds_write_b32 v155, v131 offset:1792
	s_waitcnt lgkmcnt(0)
	ds_read_b128 v[116:119], v153 offset:2048
	ds_read_b128 v[120:123], v153 offset:2176
	s_waitcnt lgkmcnt(0)
	v_sub_f32_e32 v64, v64, v116
	v_exp_f32_e32 v124, v116
	v_exp_f32_e64 v116, -v116
	v_exp_f32_e32 v64, v64
	v_sub_f32_e32 v65, v65, v117
	v_exp_f32_e32 v125, v117
	v_exp_f32_e64 v117, -v117
	v_exp_f32_e32 v65, v65
	v_sub_f32_e32 v66, v66, v118
	v_exp_f32_e32 v126, v118
	v_exp_f32_e64 v118, -v118
	v_exp_f32_e32 v66, v66
	v_sub_f32_e32 v67, v67, v119
	v_exp_f32_e32 v127, v119
	v_exp_f32_e64 v119, -v119
	v_exp_f32_e32 v67, v67
	v_sub_f32_e32 v68, v68, v120
	v_exp_f32_e32 v128, v120
	v_exp_f32_e64 v120, -v120
	v_exp_f32_e32 v68, v68
	v_sub_f32_e32 v69, v69, v121
	v_exp_f32_e32 v129, v121
	v_exp_f32_e64 v121, -v121
	v_exp_f32_e32 v69, v69
	v_sub_f32_e32 v70, v70, v122
	v_exp_f32_e32 v130, v122
	v_exp_f32_e64 v122, -v122
	v_exp_f32_e32 v70, v70
	v_sub_f32_e32 v71, v71, v123
	v_exp_f32_e32 v131, v123
	v_exp_f32_e64 v123, -v123
	v_exp_f32_e32 v71, v71
	s_nop 1
	v_pk_mul_f32 v[72:73], v[72:73], v[124:125]
	v_pk_mul_f32 v[80:81], v[80:81], v[124:125]
	v_pk_mul_f32 v[88:89], v[88:89], v[64:65]
	v_pk_mul_f32 v[96:97], v[96:97], v[116:117]
	v_pk_mul_f32 v[74:75], v[74:75], v[126:127]
	v_pk_mul_f32 v[82:83], v[82:83], v[126:127]
	v_pk_mul_f32 v[90:91], v[90:91], v[66:67]
	v_pk_mul_f32 v[98:99], v[98:99], v[118:119]
	v_pk_mul_f32 v[76:77], v[76:77], v[128:129]
	v_pk_mul_f32 v[84:85], v[84:85], v[128:129]
	v_pk_mul_f32 v[92:93], v[92:93], v[68:69]
	v_pk_mul_f32 v[100:101], v[100:101], v[120:121]
	v_pk_mul_f32 v[78:79], v[78:79], v[130:131]
	v_pk_mul_f32 v[86:87], v[86:87], v[130:131]
	v_pk_mul_f32 v[94:95], v[94:95], v[70:71]
	v_pk_mul_f32 v[102:103], v[102:103], v[122:123]
	ds_write_b128 v8, v[72:75] offset:0
	ds_write_b128 v8, v[76:79] offset:128
	ds_write_b128 v8, v[80:83] offset:256
	ds_write_b128 v8, v[84:87] offset:384
	ds_write2_b32 v138, v96, v97 offset0:1 offset1:3
	ds_write2_b32 v139, v88, v89 offset0:0 offset1:2
	ds_write2_b32 v138, v98, v99 offset0:65 offset1:67
	ds_write2_b32 v139, v90, v91 offset0:64 offset1:66
	ds_write2_b32 v138, v100, v101 offset0:33 offset1:35
	ds_write2_b32 v139, v92, v93 offset0:32 offset1:34
	ds_write2_b32 v138, v102, v103 offset0:97 offset1:99
	ds_write2_b32 v139, v94, v95 offset0:96 offset1:98
	ds_write2_b32 v142, v104, v105 offset1:36
	s_and_saveexec_b64 s[68:69], s[12:13]
	ds_write_b128 v158, v[88:91] offset:0
	ds_write_b128 v158, v[92:95] offset:128
	s_mov_b64 exec, s[68:69]
	s_and_saveexec_b64 s[68:69], s[14:15]
	ds_write_b128 v159, v[116:119] offset:0
	ds_write_b128 v159, v[120:123] offset:128
	s_mov_b64 exec, s[68:69]

.Lsc_G_wd_1:
	v_lshlrev_b32_e32 v64, 16, v54
	v_and_b32_e32 v65, 0xffff0000, v54
	v_mul_f32_e32 v64, 0x3fb8aa3b, v64
	v_mul_f32_e32 v65, 0x3fb8aa3b, v65
	v_lshlrev_b32_e32 v66, 16, v55
	v_and_b32_e32 v67, 0xffff0000, v55
	v_mul_f32_e32 v66, 0x3fb8aa3b, v66
	v_mul_f32_e32 v67, 0x3fb8aa3b, v67
	v_lshlrev_b32_e32 v68, 16, v56
	v_and_b32_e32 v69, 0xffff0000, v56
	v_mul_f32_e32 v68, 0x3fb8aa3b, v68
	v_mul_f32_e32 v69, 0x3fb8aa3b, v69
	v_lshlrev_b32_e32 v70, 16, v57
	v_and_b32_e32 v71, 0xffff0000, v57
	v_mul_f32_e32 v70, 0x3fb8aa3b, v70
	v_mul_f32_e32 v71, 0x3fb8aa3b, v71
	ds_write_b128 v153, v[64:67]
	ds_write_b128 v153, v[68:71] offset:128
	s_waitcnt lgkmcnt(0)
	ds_read_b32 v124, v154 offset:0
	ds_read_b32 v125, v154 offset:256
	ds_read_b32 v126, v154 offset:512
	ds_read_b32 v127, v154 offset:768
	ds_read_b32 v128, v154 offset:1024
	ds_read_b32 v129, v154 offset:1280
	ds_read_b32 v130, v154 offset:1536
	ds_read_b32 v131, v154 offset:1792
	v_lshlrev_b32_e32 v108, 16, v50
	v_and_b32_e32 v109, 0xffff0000, v50
	v_lshlrev_b32_e32 v110, 16, v58
	v_and_b32_e32 v111, 0xffff0000, v58
	v_lshlrev_b32_e32 v96, 16, v46
	v_and_b32_e32 v97, 0xffff0000, v46
	v_pk_add_f32 v[112:113], v[110:111], -1.0 op_sel_hi:[1,0]
	v_pk_mul_f32 v[114:115], v[12:13], v[108:109]
	v_pk_fma_f32 v[112:113], v[20:21], v[112:113], 1.0 op_sel_hi:[1,1,0]
	v_pk_mul_f32 v[88:89], v[62:63], v[114:115] op_sel_hi:[0,1]
	v_pk_mul_f32 v[72:73], v[112:113], v[108:109]
	v_pk_mul_f32 v[80:81], v[88:89], v[110:111]
	v_lshlrev_b32_e32 v108, 16, v51
	v_and_b32_e32 v109, 0xffff0000, v51
	v_lshlrev_b32_e32 v110, 16, v59
	v_and_b32_e32 v111, 0xffff0000, v59
	v_lshlrev_b32_e32 v98, 16, v47
	v_and_b32_e32 v99, 0xffff0000, v47
	v_pk_add_f32 v[112:113], v[110:111], -1.0 op_sel_hi:[1,0]
	v_pk_mul_f32 v[114:115], v[14:15], v[108:109]
	v_pk_fma_f32 v[112:113], v[22:23], v[112:113], 1.0 op_sel_hi:[1,1,0]
	v_pk_mul_f32 v[90:91], v[62:63], v[114:115] op_sel_hi:[0,1]
	v_pk_mul_f32 v[74:75], v[112:113], v[108:109]
	v_pk_mul_f32 v[82:83], v[90:91], v[110:111]
	v_lshlrev_b32_e32 v108, 16, v52
	v_and_b32_e32 v109, 0xffff0000, v52
	v_lshlrev_b32_e32 v110, 16, v60
	v_and_b32_e32 v111, 0xffff0000, v60
	v_lshlrev_b32_e32 v100, 16, v48
	v_and_b32_e32 v101, 0xffff0000, v48
	v_pk_add_f32 v[112:113], v[110:111], -1.0 op_sel_hi:[1,0]
	v_pk_mul_f32 v[114:115], v[16:17], v[108:109]
	v_pk_fma_f32 v[112:113], v[24:25], v[112:113], 1.0 op_sel_hi:[1,1,0]
	v_pk_mul_f32 v[92:93], v[62:63], v[114:115] op_sel_hi:[0,1]
	v_pk_mul_f32 v[76:77], v[112:113], v[108:109]
	v_pk_mul_f32 v[84:85], v[92:93], v[110:111]
	v_lshlrev_b32_e32 v108, 16, v53
	v_and_b32_e32 v109, 0xffff0000, v53
	v_lshlrev_b32_e32 v110, 16, v61
	v_and_b32_e32 v111, 0xffff0000, v61
	v_lshlrev_b32_e32 v102, 16, v49
	v_and_b32_e32 v103, 0xffff0000, v49
	v_pk_add_f32 v[112:113], v[110:111], -1.0 op_sel_hi:[1,0]
	v_pk_mul_f32 v[114:115], v[18:19], v[108:109]
	v_pk_fma_f32 v[112:113], v[26:27], v[112:113], 1.0 op_sel_hi:[1,1,0]
	v_pk_mul_f32 v[94:95], v[62:63], v[114:115] op_sel_hi:[0,1]
	v_pk_mul_f32 v[78:79], v[112:113], v[108:109]
	v_pk_mul_f32 v[86:87], v[94:95], v[110:111]
	v_lshlrev_b32_e32 v104, 16, v63
	v_and_b32_e32 v105, 0xffff0000, v63
	s_waitcnt lgkmcnt(0)
	v_add_f32_e32 v125, v124, v125
	v_add_f32_e32 v126, v125, v126
	v_add_f32_e32 v127, v126, v127
	v_add_f32_e32 v128, v127, v128
	v_add_f32_e32 v129, v128, v129
	v_add_f32_e32 v130, v129, v130
	v_add_f32_e32 v131, v130, v131
	ds_write_b32 v155, v124 offset:0
	ds_write_b32 v155, v125 offset:256
	ds_write_b32 v155, v126 offset:512
	ds_write_b32 v155, v127 offset:768
	ds_write_b32 v155, v128 offset:1024
	ds_write_b32 v155, v129 offset:1280
	ds_write_b32 v155, v130 offset:1536
	ds_write_b32 v155, v131 offset:1792
	s_waitcnt lgkmcnt(0)
	ds_read_b128 v[116:119], v153 offset:2048
	ds_read_b128 v[120:123], v153 offset:2176
	s_waitcnt lgkmcnt(0)
	v_sub_f32_e32 v64, v64, v116
	v_exp_f32_e32 v124, v116
	v_exp_f32_e64 v116, -v116
	v_exp_f32_e32 v64, v64
	v_sub_f32_e32 v65, v65, v117
	v_exp_f32_e32 v125, v117
	v_exp_f32_e64 v117, -v117
	v_exp_f32_e32 v65, v65
	v_sub_f32_e32 v66, v66, v118
	v_exp_f32_e32 v126, v118
	v_exp_f32_e64 v118, -v118
	v_exp_f32_e32 v66, v66
	v_sub_f32_e32 v67, v67, v119
	v_exp_f32_e32 v127, v119
	v_exp_f32_e64 v119, -v119
	v_exp_f32_e32 v67, v67
	v_sub_f32_e32 v68, v68, v120
	v_exp_f32_e32 v128, v120
	v_exp_f32_e64 v120, -v120
	v_exp_f32_e32 v68, v68
	v_sub_f32_e32 v69, v69, v121
	v_exp_f32_e32 v129, v121
	v_exp_f32_e64 v121, -v121
	v_exp_f32_e32 v69, v69
	v_sub_f32_e32 v70, v70, v122
	v_exp_f32_e32 v130, v122
	v_exp_f32_e64 v122, -v122
	v_exp_f32_e32 v70, v70
	v_sub_f32_e32 v71, v71, v123
	v_exp_f32_e32 v131, v123
	v_exp_f32_e64 v123, -v123
	v_exp_f32_e32 v71, v71
	s_nop 1
	v_pk_mul_f32 v[72:73], v[72:73], v[124:125]
	v_pk_mul_f32 v[80:81], v[80:81], v[124:125]
	v_pk_mul_f32 v[88:89], v[88:89], v[64:65]
	v_pk_mul_f32 v[96:97], v[96:97], v[116:117]
	v_pk_mul_f32 v[74:75], v[74:75], v[126:127]
	v_pk_mul_f32 v[82:83], v[82:83], v[126:127]
	v_pk_mul_f32 v[90:91], v[90:91], v[66:67]
	v_pk_mul_f32 v[98:99], v[98:99], v[118:119]
	v_pk_mul_f32 v[76:77], v[76:77], v[128:129]
	v_pk_mul_f32 v[84:85], v[84:85], v[128:129]
	v_pk_mul_f32 v[92:93], v[92:93], v[68:69]
	v_pk_mul_f32 v[100:101], v[100:101], v[120:121]
	v_pk_mul_f32 v[78:79], v[78:79], v[130:131]
	v_pk_mul_f32 v[86:87], v[86:87], v[130:131]
	v_pk_mul_f32 v[94:95], v[94:95], v[70:71]
	v_pk_mul_f32 v[102:103], v[102:103], v[122:123]
	ds_write_b128 v8, v[72:75] offset:34816
	ds_write_b128 v8, v[76:79] offset:34944
	ds_write_b128 v8, v[80:83] offset:35072
	ds_write_b128 v8, v[84:87] offset:35200
	ds_write2_b32 v140, v96, v97 offset0:1 offset1:3
	ds_write2_b32 v141, v88, v89 offset0:0 offset1:2
	ds_write2_b32 v140, v98, v99 offset0:65 offset1:67
	ds_write2_b32 v141, v90, v91 offset0:64 offset1:66
	ds_write2_b32 v140, v100, v101 offset0:33 offset1:35
	ds_write2_b32 v141, v92, v93 offset0:32 offset1:34
	ds_write2_b32 v140, v102, v103 offset0:97 offset1:99
	ds_write2_b32 v141, v94, v95 offset0:96 offset1:98
	ds_write2_b32 v143, v104, v105 offset1:36
	s_and_saveexec_b64 s[68:69], s[12:13]
	ds_write_b128 v158, v[88:91] offset:34816
	ds_write_b128 v158, v[92:95] offset:34944
	s_mov_b64 exec, s[68:69]
	s_and_saveexec_b64 s[68:69], s[14:15]
	ds_write_b128 v159, v[116:119] offset:34816
	ds_write_b128 v159, v[120:123] offset:34944
	s_mov_b64 exec, s[68:69]
